# scan loops (consumer with loads-at-head/wait-per-2/deferred transposes, producer) with every 8-byte instruction 8-byte aligned (e64 encodings + 47 s_nop pads)
# speedup vs baseline: 1.0230x; 1.0064x over previous
.Lscan_cons_chunk:
	s_nop 0
	v_cndmask_b32_e64 v2, v4, v5, s[42:43]
	v_add_lshl_u32 v2, v2, s80, 10
	v_mov_b32_e64 v3, v180
	s_add_i32 s28, s28, 0x10000
	v_lshl_add_u64 v[2:3], v[0:1], 0, v[2:3]
	v_add_u32_e64 v5, 64, v5
	v_subrev_u32_e64 v4, 64, v4
	s_waitcnt lgkmcnt(0)
	s_nop 0
	ds_read_b128 v[88:91], v10 offset:2304
	ds_read_b128 v[96:99], v10 offset:2816
	ds_read_b128 v[92:95], v10 offset:2560
	v_fma_mix_f32 v12, v6, v20, v180 op_sel_hi:[0,1,0]
	v_fma_mix_f32 v12, v7, v20, v12 op_sel:[0,1,0] op_sel_hi:[0,1,0]
	v_fma_mix_f32 v12, v8, v21, v12 op_sel_hi:[0,1,0]
	v_fma_mix_f32 v12, v9, v21, v12 op_sel:[0,1,0] op_sel_hi:[0,1,0]
	s_nop 1
	s_nop 0
	v_add_f32_dpp v12, v12, v12 row_ror:1 row_mask:0xf bank_mask:0xf bound_ctrl:1
	s_nop 1
	s_nop 0
	v_add_f32_dpp v12, v12, v12 row_ror:2 row_mask:0xf bank_mask:0xf bound_ctrl:1
	v_pk_fma_f32 v[48:49], v[28:29], v[66:67], v[6:7] op_sel_hi:[1,0,1]
	v_pk_fma_f32 v[50:51], v[30:31], v[66:67], v[8:9] op_sel_hi:[1,0,1]
	v_add_f32_dpp v12, v12, v12 row_ror:4 row_mask:0xf bank_mask:0xf bound_ctrl:1
	v_add_f32_dpp v130, v130, v130 row_ror:8 row_mask:0xf bank_mask:0xc
	v_add_f32_dpp v130, v122, v122 row_ror:8 row_mask:0xf bank_mask:0x3
	v_add_f32_dpp v131, v131, v131 row_ror:8 row_mask:0xf bank_mask:0xc
	v_add_f32_dpp v12, v12, v12 row_ror:8 row_mask:0xf bank_mask:0xf bound_ctrl:1
	v_pk_fma_f32 v[6:7], v[24:25], v[12:13], v[48:49] op_sel_hi:[1,0,1] neg_lo:[1,0,0] neg_hi:[1,0,0]
	v_pk_fma_f32 v[8:9], v[26:27], v[12:13], v[50:51] op_sel_hi:[1,0,1] neg_lo:[1,0,0] neg_hi:[1,0,0]
	ds_read_b128 v[110:113], v10 offset:3328
	ds_read_b128 v[106:109], v10 offset:3072
	ds_read_b128 v[118:121], v10 offset:3840
	ds_read_b128 v[114:117], v10 offset:3584
	ds_read_b128 v[70:73], v11 offset:256
	v_fma_mix_f32 v12, v6, v36, v180 op_sel_hi:[0,1,0]
	v_fma_mix_f32 v12, v7, v36, v12 op_sel:[0,1,0] op_sel_hi:[0,1,0]
	v_fma_mix_f32 v12, v8, v37, v12 op_sel_hi:[0,1,0]
	v_fma_mix_f32 v12, v9, v37, v12 op_sel:[0,1,0] op_sel_hi:[0,1,0]
	v_fma_mix_f32 v52, v6, v22, v180 op_sel_hi:[0,1,0]
	v_fma_mix_f32 v52, v7, v22, v52 op_sel:[0,1,0] op_sel_hi:[0,1,0]
	v_add_f32_dpp v12, v12, v12 row_ror:1 row_mask:0xf bank_mask:0xf bound_ctrl:1
	v_fma_mix_f32 v52, v8, v23, v52 op_sel_hi:[0,1,0]
	v_fma_mix_f32 v52, v9, v23, v52 op_sel:[0,1,0] op_sel_hi:[0,1,0]
	v_add_f32_dpp v12, v12, v12 row_ror:2 row_mask:0xf bank_mask:0xf bound_ctrl:1
	v_pk_fma_f32 v[48:49], v[44:45], v[66:67], v[6:7] op_sel:[0,1,0]
	v_pk_fma_f32 v[50:51], v[46:47], v[66:67], v[8:9] op_sel:[0,1,0]
	v_add_f32_dpp v12, v12, v12 row_ror:4 row_mask:0xf bank_mask:0xf bound_ctrl:1
	v_add_f32_dpp v131, v123, v123 row_ror:8 row_mask:0xf bank_mask:0x3
	v_add_f32_dpp v132, v132, v132 row_ror:8 row_mask:0xf bank_mask:0xc
	v_add_f32_dpp v132, v124, v124 row_ror:8 row_mask:0xf bank_mask:0x3
	v_add_f32_dpp v12, v12, v12 row_ror:8 row_mask:0xf bank_mask:0xf bound_ctrl:1
	v_pk_fma_f32 v[6:7], v[40:41], v[12:13], v[48:49] op_sel_hi:[1,0,1] neg_lo:[1,0,0] neg_hi:[1,0,0]
	v_pk_fma_f32 v[8:9], v[42:43], v[12:13], v[50:51] op_sel_hi:[1,0,1] neg_lo:[1,0,0] neg_hi:[1,0,0]
	s_waitcnt lgkmcnt(1)
	s_nop 0
	ds_read_b128 v[20:23], v10 offset:4352
	ds_read_b128 v[28:31], v10 offset:4864
	ds_read_b128 v[24:27], v10 offset:4608
	v_fma_mix_f32 v12, v6, v88, v180 op_sel_hi:[0,1,0]
	v_fma_mix_f32 v12, v7, v88, v12 op_sel:[0,1,0] op_sel_hi:[0,1,0]
	v_fma_mix_f32 v12, v8, v89, v12 op_sel_hi:[0,1,0]
	v_fma_mix_f32 v12, v9, v89, v12 op_sel:[0,1,0] op_sel_hi:[0,1,0]
	v_fma_mix_f32 v53, v6, v38, v180 op_sel_hi:[0,1,0]
	v_fma_mix_f32 v53, v7, v38, v53 op_sel:[0,1,0] op_sel_hi:[0,1,0]
	v_add_f32_dpp v12, v12, v12 row_ror:1 row_mask:0xf bank_mask:0xf bound_ctrl:1
	v_fma_mix_f32 v53, v8, v39, v53 op_sel_hi:[0,1,0]
	v_fma_mix_f32 v53, v9, v39, v53 op_sel:[0,1,0] op_sel_hi:[0,1,0]
	v_add_f32_dpp v12, v12, v12 row_ror:2 row_mask:0xf bank_mask:0xf bound_ctrl:1
	v_pk_fma_f32 v[48:49], v[96:97], v[68:69], v[6:7] op_sel_hi:[1,0,1]
	v_pk_fma_f32 v[50:51], v[98:99], v[68:69], v[8:9] op_sel_hi:[1,0,1]
	v_add_f32_dpp v12, v12, v12 row_ror:4 row_mask:0xf bank_mask:0xf bound_ctrl:1
	v_add_f32_dpp v133, v133, v133 row_ror:8 row_mask:0xf bank_mask:0xc
	v_add_f32_dpp v133, v125, v125 row_ror:8 row_mask:0xf bank_mask:0x3
	v_add_f32_dpp v134, v134, v134 row_ror:8 row_mask:0xf bank_mask:0xc
	v_add_f32_dpp v12, v12, v12 row_ror:8 row_mask:0xf bank_mask:0xf bound_ctrl:1
	v_pk_fma_f32 v[6:7], v[92:93], v[12:13], v[48:49] op_sel_hi:[1,0,1] neg_lo:[1,0,0] neg_hi:[1,0,0]
	v_pk_fma_f32 v[8:9], v[94:95], v[12:13], v[50:51] op_sel_hi:[1,0,1] neg_lo:[1,0,0] neg_hi:[1,0,0]
	ds_read_b128 v[36:39], v10 offset:5376
	ds_read_b128 v[44:47], v10 offset:5888
	ds_read_b128 v[40:43], v10 offset:5632
	v_fma_mix_f32 v12, v6, v110, v180 op_sel_hi:[0,1,0]
	v_fma_mix_f32 v12, v7, v110, v12 op_sel:[0,1,0] op_sel_hi:[0,1,0]
	v_fma_mix_f32 v12, v8, v111, v12 op_sel_hi:[0,1,0]
	v_fma_mix_f32 v12, v9, v111, v12 op_sel:[0,1,0] op_sel_hi:[0,1,0]
	v_fma_mix_f32 v54, v6, v90, v180 op_sel_hi:[0,1,0]
	v_fma_mix_f32 v54, v7, v90, v54 op_sel:[0,1,0] op_sel_hi:[0,1,0]
	v_add_f32_dpp v12, v12, v12 row_ror:1 row_mask:0xf bank_mask:0xf bound_ctrl:1
	v_fma_mix_f32 v54, v8, v91, v54 op_sel_hi:[0,1,0]
	v_fma_mix_f32 v54, v9, v91, v54 op_sel:[0,1,0] op_sel_hi:[0,1,0]
	v_add_f32_dpp v12, v12, v12 row_ror:2 row_mask:0xf bank_mask:0xf bound_ctrl:1
	v_pk_fma_f32 v[48:49], v[118:119], v[68:69], v[6:7] op_sel:[0,1,0]
	v_pk_fma_f32 v[50:51], v[120:121], v[68:69], v[8:9] op_sel:[0,1,0]
	v_add_f32_dpp v12, v12, v12 row_ror:4 row_mask:0xf bank_mask:0xf bound_ctrl:1
	v_add_f32_dpp v134, v126, v126 row_ror:8 row_mask:0xf bank_mask:0x3
	v_add_f32_dpp v135, v135, v135 row_ror:8 row_mask:0xf bank_mask:0xc
	v_add_f32_dpp v135, v127, v127 row_ror:8 row_mask:0xf bank_mask:0x3
	v_add_f32_dpp v12, v12, v12 row_ror:8 row_mask:0xf bank_mask:0xf bound_ctrl:1
	v_pk_fma_f32 v[6:7], v[114:115], v[12:13], v[48:49] op_sel_hi:[1,0,1] neg_lo:[1,0,0] neg_hi:[1,0,0]
	v_pk_fma_f32 v[8:9], v[116:117], v[12:13], v[50:51] op_sel_hi:[1,0,1] neg_lo:[1,0,0] neg_hi:[1,0,0]
	v_pk_mul_f32 v[6:7], v[6:7], v[106:107]
	v_pk_mul_f32 v[8:9], v[8:9], v[108:109]
	s_waitcnt lgkmcnt(0)
	s_nop 0
	ds_read_b128 v[88:91], v10 offset:6400
	ds_read_b128 v[96:99], v10 offset:6912
	ds_read_b128 v[92:95], v10 offset:6656
	v_fma_mix_f32 v12, v6, v20, v180 op_sel_hi:[0,1,0]
	v_fma_mix_f32 v12, v7, v20, v12 op_sel:[0,1,0] op_sel_hi:[0,1,0]
	v_fma_mix_f32 v12, v8, v21, v12 op_sel_hi:[0,1,0]
	v_fma_mix_f32 v12, v9, v21, v12 op_sel:[0,1,0] op_sel_hi:[0,1,0]
	v_fma_mix_f32 v55, v6, v112, v180 op_sel_hi:[0,1,0]
	v_fma_mix_f32 v55, v7, v112, v55 op_sel:[0,1,0] op_sel_hi:[0,1,0]
	v_add_f32_dpp v12, v12, v12 row_ror:1 row_mask:0xf bank_mask:0xf bound_ctrl:1
	v_fma_mix_f32 v55, v8, v113, v55 op_sel_hi:[0,1,0]
	v_fma_mix_f32 v55, v9, v113, v55 op_sel:[0,1,0] op_sel_hi:[0,1,0]
	v_add_f32_dpp v12, v12, v12 row_ror:2 row_mask:0xf bank_mask:0xf bound_ctrl:1
	v_pk_fma_f32 v[48:49], v[28:29], v[70:71], v[6:7] op_sel_hi:[1,0,1]
	v_pk_fma_f32 v[50:51], v[30:31], v[70:71], v[8:9] op_sel_hi:[1,0,1]
	v_add_f32_dpp v12, v12, v12 row_ror:4 row_mask:0xf bank_mask:0xf bound_ctrl:1
	v_add_f32_dpp v136, v136, v136 row_ror:8 row_mask:0xf bank_mask:0xc
	v_add_f32_dpp v136, v128, v128 row_ror:8 row_mask:0xf bank_mask:0x3
	v_add_f32_dpp v12, v12, v12 row_ror:8 row_mask:0xf bank_mask:0xf bound_ctrl:1
	v_pk_fma_f32 v[6:7], v[24:25], v[12:13], v[48:49] op_sel_hi:[1,0,1] neg_lo:[1,0,0] neg_hi:[1,0,0]
	v_pk_fma_f32 v[8:9], v[26:27], v[12:13], v[50:51] op_sel_hi:[1,0,1] neg_lo:[1,0,0] neg_hi:[1,0,0]
	ds_read_b128 v[110:113], v10 offset:7424
	ds_read_b128 v[106:109], v10 offset:7168
	ds_read_b128 v[118:121], v10 offset:7936
	ds_read_b128 v[114:117], v10 offset:7680
	ds_read_b128 v[66:69], v11 offset:512
	v_fma_mix_f32 v12, v6, v36, v180 op_sel_hi:[0,1,0]
	v_fma_mix_f32 v12, v7, v36, v12 op_sel:[0,1,0] op_sel_hi:[0,1,0]
	v_fma_mix_f32 v12, v8, v37, v12 op_sel_hi:[0,1,0]
	v_fma_mix_f32 v12, v9, v37, v12 op_sel:[0,1,0] op_sel_hi:[0,1,0]
	v_fma_mix_f32 v56, v6, v22, v180 op_sel_hi:[0,1,0]
	v_fma_mix_f32 v56, v7, v22, v56 op_sel:[0,1,0] op_sel_hi:[0,1,0]
	v_add_f32_dpp v12, v12, v12 row_ror:1 row_mask:0xf bank_mask:0xf bound_ctrl:1
	v_fma_mix_f32 v56, v8, v23, v56 op_sel_hi:[0,1,0]
	v_fma_mix_f32 v56, v9, v23, v56 op_sel:[0,1,0] op_sel_hi:[0,1,0]
	v_add_f32_dpp v12, v12, v12 row_ror:2 row_mask:0xf bank_mask:0xf bound_ctrl:1
	v_pk_fma_f32 v[48:49], v[44:45], v[70:71], v[6:7] op_sel:[0,1,0]
	v_pk_fma_f32 v[50:51], v[46:47], v[70:71], v[8:9] op_sel:[0,1,0]
	v_add_f32_dpp v12, v12, v12 row_ror:4 row_mask:0xf bank_mask:0xf bound_ctrl:1
	v_add_f32_dpp v137, v137, v137 row_ror:8 row_mask:0xf bank_mask:0xc
	v_add_f32_dpp v137, v129, v129 row_ror:8 row_mask:0xf bank_mask:0x3
	v_add_f32_dpp v12, v12, v12 row_ror:8 row_mask:0xf bank_mask:0xf bound_ctrl:1
	v_pk_fma_f32 v[6:7], v[40:41], v[12:13], v[48:49] op_sel_hi:[1,0,1] neg_lo:[1,0,0] neg_hi:[1,0,0]
	v_pk_fma_f32 v[8:9], v[42:43], v[12:13], v[50:51] op_sel_hi:[1,0,1] neg_lo:[1,0,0] neg_hi:[1,0,0]
	s_waitcnt lgkmcnt(1)
	s_nop 0
	ds_read_b128 v[20:23], v10 offset:8448
	ds_read_b128 v[28:31], v10 offset:8960
	ds_read_b128 v[24:27], v10 offset:8704
	v_fma_mix_f32 v12, v6, v88, v180 op_sel_hi:[0,1,0]
	v_fma_mix_f32 v12, v7, v88, v12 op_sel:[0,1,0] op_sel_hi:[0,1,0]
	v_fma_mix_f32 v12, v8, v89, v12 op_sel_hi:[0,1,0]
	v_fma_mix_f32 v12, v9, v89, v12 op_sel:[0,1,0] op_sel_hi:[0,1,0]
	v_fma_mix_f32 v57, v6, v38, v180 op_sel_hi:[0,1,0]
	v_fma_mix_f32 v57, v7, v38, v57 op_sel:[0,1,0] op_sel_hi:[0,1,0]
	v_add_f32_dpp v12, v12, v12 row_ror:1 row_mask:0xf bank_mask:0xf bound_ctrl:1
	v_fma_mix_f32 v57, v8, v39, v57 op_sel_hi:[0,1,0]
	v_fma_mix_f32 v57, v9, v39, v57 op_sel:[0,1,0] op_sel_hi:[0,1,0]
	v_add_f32_dpp v12, v12, v12 row_ror:2 row_mask:0xf bank_mask:0xf bound_ctrl:1
	v_pk_fma_f32 v[48:49], v[96:97], v[72:73], v[6:7] op_sel_hi:[1,0,1]
	v_pk_fma_f32 v[50:51], v[98:99], v[72:73], v[8:9] op_sel_hi:[1,0,1]
	v_add_f32_dpp v12, v12, v12 row_ror:4 row_mask:0xf bank_mask:0xf bound_ctrl:1
	v_add_f32_dpp v134, v134, v134 row_ror:4 row_mask:0xf bank_mask:0xa
	v_add_f32_dpp v134, v130, v130 row_ror:12 row_mask:0xf bank_mask:0x5
	v_add_f32_dpp v135, v135, v135 row_ror:4 row_mask:0xf bank_mask:0xa
	v_add_f32_dpp v12, v12, v12 row_ror:8 row_mask:0xf bank_mask:0xf bound_ctrl:1
	v_pk_fma_f32 v[6:7], v[92:93], v[12:13], v[48:49] op_sel_hi:[1,0,1] neg_lo:[1,0,0] neg_hi:[1,0,0]
	v_pk_fma_f32 v[8:9], v[94:95], v[12:13], v[50:51] op_sel_hi:[1,0,1] neg_lo:[1,0,0] neg_hi:[1,0,0]
	ds_read_b128 v[36:39], v10 offset:9472
	ds_read_b128 v[44:47], v10 offset:9984
	ds_read_b128 v[40:43], v10 offset:9728
	v_fma_mix_f32 v12, v6, v110, v180 op_sel_hi:[0,1,0]
	v_fma_mix_f32 v12, v7, v110, v12 op_sel:[0,1,0] op_sel_hi:[0,1,0]
	v_fma_mix_f32 v12, v8, v111, v12 op_sel_hi:[0,1,0]
	v_fma_mix_f32 v12, v9, v111, v12 op_sel:[0,1,0] op_sel_hi:[0,1,0]
	v_fma_mix_f32 v81, v6, v90, v180 op_sel_hi:[0,1,0]
	v_fma_mix_f32 v81, v7, v90, v81 op_sel:[0,1,0] op_sel_hi:[0,1,0]
	v_add_f32_dpp v12, v12, v12 row_ror:1 row_mask:0xf bank_mask:0xf bound_ctrl:1
	v_fma_mix_f32 v81, v8, v91, v81 op_sel_hi:[0,1,0]
	v_fma_mix_f32 v81, v9, v91, v81 op_sel:[0,1,0] op_sel_hi:[0,1,0]
	v_add_f32_dpp v12, v12, v12 row_ror:2 row_mask:0xf bank_mask:0xf bound_ctrl:1
	v_pk_fma_f32 v[48:49], v[118:119], v[72:73], v[6:7] op_sel:[0,1,0]
	v_pk_fma_f32 v[50:51], v[120:121], v[72:73], v[8:9] op_sel:[0,1,0]
	v_add_f32_dpp v12, v12, v12 row_ror:4 row_mask:0xf bank_mask:0xf bound_ctrl:1
	v_add_f32_dpp v135, v131, v131 row_ror:12 row_mask:0xf bank_mask:0x5
	v_add_f32_dpp v136, v136, v136 row_ror:4 row_mask:0xf bank_mask:0xa
	v_add_f32_dpp v136, v132, v132 row_ror:12 row_mask:0xf bank_mask:0x5
	v_add_f32_dpp v12, v12, v12 row_ror:8 row_mask:0xf bank_mask:0xf bound_ctrl:1
	v_pk_fma_f32 v[6:7], v[114:115], v[12:13], v[48:49] op_sel_hi:[1,0,1] neg_lo:[1,0,0] neg_hi:[1,0,0]
	v_pk_fma_f32 v[8:9], v[116:117], v[12:13], v[50:51] op_sel_hi:[1,0,1] neg_lo:[1,0,0] neg_hi:[1,0,0]
	v_pk_mul_f32 v[6:7], v[6:7], v[106:107]
	v_pk_mul_f32 v[8:9], v[8:9], v[108:109]
	s_waitcnt lgkmcnt(0)
	s_nop 0
	ds_read_b128 v[88:91], v10 offset:10496
	ds_read_b128 v[96:99], v10 offset:11008
	ds_read_b128 v[92:95], v10 offset:10752
	v_fma_mix_f32 v12, v6, v20, v180 op_sel_hi:[0,1,0]
	v_fma_mix_f32 v12, v7, v20, v12 op_sel:[0,1,0] op_sel_hi:[0,1,0]
	v_fma_mix_f32 v12, v8, v21, v12 op_sel_hi:[0,1,0]
	v_fma_mix_f32 v12, v9, v21, v12 op_sel:[0,1,0] op_sel_hi:[0,1,0]
	v_fma_mix_f32 v82, v6, v112, v180 op_sel_hi:[0,1,0]
	v_fma_mix_f32 v82, v7, v112, v82 op_sel:[0,1,0] op_sel_hi:[0,1,0]
	v_add_f32_dpp v12, v12, v12 row_ror:1 row_mask:0xf bank_mask:0xf bound_ctrl:1
	v_fma_mix_f32 v82, v8, v113, v82 op_sel_hi:[0,1,0]
	v_fma_mix_f32 v82, v9, v113, v82 op_sel:[0,1,0] op_sel_hi:[0,1,0]
	v_add_f32_dpp v12, v12, v12 row_ror:2 row_mask:0xf bank_mask:0xf bound_ctrl:1
	v_pk_fma_f32 v[48:49], v[28:29], v[66:67], v[6:7] op_sel_hi:[1,0,1]
	v_pk_fma_f32 v[50:51], v[30:31], v[66:67], v[8:9] op_sel_hi:[1,0,1]
	v_add_f32_dpp v12, v12, v12 row_ror:4 row_mask:0xf bank_mask:0xf bound_ctrl:1
	v_add_f32_dpp v137, v137, v137 row_ror:4 row_mask:0xf bank_mask:0xa
	v_add_f32_dpp v137, v133, v133 row_ror:12 row_mask:0xf bank_mask:0x5
	v_add_f32_dpp v12, v12, v12 row_ror:8 row_mask:0xf bank_mask:0xf bound_ctrl:1
	v_pk_fma_f32 v[6:7], v[24:25], v[12:13], v[48:49] op_sel_hi:[1,0,1] neg_lo:[1,0,0] neg_hi:[1,0,0]
	v_pk_fma_f32 v[8:9], v[26:27], v[12:13], v[50:51] op_sel_hi:[1,0,1] neg_lo:[1,0,0] neg_hi:[1,0,0]
	ds_read_b128 v[110:113], v10 offset:11520
	ds_read_b128 v[106:109], v10 offset:11264
	ds_read_b128 v[118:121], v10 offset:12032
	ds_read_b128 v[114:117], v10 offset:11776
	ds_read_b128 v[70:73], v11 offset:768
	v_fma_mix_f32 v12, v6, v36, v180 op_sel_hi:[0,1,0]
	v_fma_mix_f32 v12, v7, v36, v12 op_sel:[0,1,0] op_sel_hi:[0,1,0]
	v_fma_mix_f32 v12, v8, v37, v12 op_sel_hi:[0,1,0]
	v_fma_mix_f32 v12, v9, v37, v12 op_sel:[0,1,0] op_sel_hi:[0,1,0]
	v_fma_mix_f32 v83, v6, v22, v180 op_sel_hi:[0,1,0]
	v_fma_mix_f32 v83, v7, v22, v83 op_sel:[0,1,0] op_sel_hi:[0,1,0]
	v_add_f32_dpp v12, v12, v12 row_ror:1 row_mask:0xf bank_mask:0xf bound_ctrl:1
	v_fma_mix_f32 v83, v8, v23, v83 op_sel_hi:[0,1,0]
	v_fma_mix_f32 v83, v9, v23, v83 op_sel:[0,1,0] op_sel_hi:[0,1,0]
	v_add_f32_dpp v12, v12, v12 row_ror:2 row_mask:0xf bank_mask:0xf bound_ctrl:1
	v_pk_fma_f32 v[48:49], v[44:45], v[66:67], v[6:7] op_sel:[0,1,0]
	v_pk_fma_f32 v[50:51], v[46:47], v[66:67], v[8:9] op_sel:[0,1,0]
	v_add_f32_dpp v12, v12, v12 row_ror:4 row_mask:0xf bank_mask:0xf bound_ctrl:1
	v_cndmask_b32_e64 v62, v136, v134, s[38:39]
	v_cndmask_b32_e64 v63, v134, v136, s[38:39]
	v_add_f32_dpp v12, v12, v12 row_ror:8 row_mask:0xf bank_mask:0xf bound_ctrl:1
	v_pk_fma_f32 v[6:7], v[40:41], v[12:13], v[48:49] op_sel_hi:[1,0,1] neg_lo:[1,0,0] neg_hi:[1,0,0]
	v_pk_fma_f32 v[8:9], v[42:43], v[12:13], v[50:51] op_sel_hi:[1,0,1] neg_lo:[1,0,0] neg_hi:[1,0,0]
	s_waitcnt lgkmcnt(1)
	s_nop 0
	ds_read_b128 v[20:23], v10 offset:12544
	ds_read_b128 v[28:31], v10 offset:13056
	ds_read_b128 v[24:27], v10 offset:12800
	v_fma_mix_f32 v12, v6, v88, v180 op_sel_hi:[0,1,0]
	v_fma_mix_f32 v12, v7, v88, v12 op_sel:[0,1,0] op_sel_hi:[0,1,0]
	v_fma_mix_f32 v12, v8, v89, v12 op_sel_hi:[0,1,0]
	v_fma_mix_f32 v12, v9, v89, v12 op_sel:[0,1,0] op_sel_hi:[0,1,0]
	v_fma_mix_f32 v100, v6, v38, v180 op_sel_hi:[0,1,0]
	v_fma_mix_f32 v100, v7, v38, v100 op_sel:[0,1,0] op_sel_hi:[0,1,0]
	v_add_f32_dpp v12, v12, v12 row_ror:1 row_mask:0xf bank_mask:0xf bound_ctrl:1
	v_fma_mix_f32 v100, v8, v39, v100 op_sel_hi:[0,1,0]
	v_fma_mix_f32 v100, v9, v39, v100 op_sel:[0,1,0] op_sel_hi:[0,1,0]
	v_add_f32_dpp v12, v12, v12 row_ror:2 row_mask:0xf bank_mask:0xf bound_ctrl:1
	v_pk_fma_f32 v[48:49], v[96:97], v[68:69], v[6:7] op_sel_hi:[1,0,1]
	v_pk_fma_f32 v[50:51], v[98:99], v[68:69], v[8:9] op_sel_hi:[1,0,1]
	v_add_f32_dpp v12, v12, v12 row_ror:4 row_mask:0xf bank_mask:0xf bound_ctrl:1
	v_cndmask_b32_e64 v64, v137, v135, s[38:39]
	v_cndmask_b32_e64 v65, v135, v137, s[38:39]
	v_add_f32_dpp v12, v12, v12 row_ror:8 row_mask:0xf bank_mask:0xf bound_ctrl:1
	v_pk_fma_f32 v[6:7], v[92:93], v[12:13], v[48:49] op_sel_hi:[1,0,1] neg_lo:[1,0,0] neg_hi:[1,0,0]
	v_pk_fma_f32 v[8:9], v[94:95], v[12:13], v[50:51] op_sel_hi:[1,0,1] neg_lo:[1,0,0] neg_hi:[1,0,0]
	ds_read_b128 v[36:39], v10 offset:13568
	ds_read_b128 v[44:47], v10 offset:14080
	ds_read_b128 v[40:43], v10 offset:13824
	v_fma_mix_f32 v12, v6, v110, v180 op_sel_hi:[0,1,0]
	v_fma_mix_f32 v12, v7, v110, v12 op_sel:[0,1,0] op_sel_hi:[0,1,0]
	v_fma_mix_f32 v12, v8, v111, v12 op_sel_hi:[0,1,0]
	v_fma_mix_f32 v12, v9, v111, v12 op_sel:[0,1,0] op_sel_hi:[0,1,0]
	v_fma_mix_f32 v101, v6, v90, v180 op_sel_hi:[0,1,0]
	v_fma_mix_f32 v101, v7, v90, v101 op_sel:[0,1,0] op_sel_hi:[0,1,0]
	v_add_f32_dpp v12, v12, v12 row_ror:1 row_mask:0xf bank_mask:0xf bound_ctrl:1
	v_fma_mix_f32 v101, v8, v91, v101 op_sel_hi:[0,1,0]
	v_fma_mix_f32 v101, v9, v91, v101 op_sel:[0,1,0] op_sel_hi:[0,1,0]
	v_add_f32_dpp v12, v12, v12 row_ror:2 row_mask:0xf bank_mask:0xf bound_ctrl:1
	v_pk_fma_f32 v[48:49], v[118:119], v[68:69], v[6:7] op_sel:[0,1,0]
	v_pk_fma_f32 v[50:51], v[120:121], v[68:69], v[8:9] op_sel:[0,1,0]
	v_add_f32_dpp v12, v12, v12 row_ror:4 row_mask:0xf bank_mask:0xf bound_ctrl:1
	v_add_f32_dpp v62, v63, v62 quad_perm:[2,3,0,1] row_mask:0xf bank_mask:0xf bound_ctrl:1
	v_add_f32_dpp v63, v65, v64 quad_perm:[2,3,0,1] row_mask:0xf bank_mask:0xf bound_ctrl:1
	v_add_f32_dpp v12, v12, v12 row_ror:8 row_mask:0xf bank_mask:0xf bound_ctrl:1
	v_pk_fma_f32 v[6:7], v[114:115], v[12:13], v[48:49] op_sel_hi:[1,0,1] neg_lo:[1,0,0] neg_hi:[1,0,0]
	v_pk_fma_f32 v[8:9], v[116:117], v[12:13], v[50:51] op_sel_hi:[1,0,1] neg_lo:[1,0,0] neg_hi:[1,0,0]
	v_pk_mul_f32 v[6:7], v[6:7], v[106:107]
	v_pk_mul_f32 v[8:9], v[8:9], v[108:109]
	s_waitcnt lgkmcnt(0)
	s_nop 0
	ds_read_b128 v[88:91], v10 offset:14592
	ds_read_b128 v[96:99], v10 offset:15104
	ds_read_b128 v[92:95], v10 offset:14848
	v_fma_mix_f32 v12, v6, v20, v180 op_sel_hi:[0,1,0]
	v_fma_mix_f32 v12, v7, v20, v12 op_sel:[0,1,0] op_sel_hi:[0,1,0]
	v_fma_mix_f32 v12, v8, v21, v12 op_sel_hi:[0,1,0]
	v_fma_mix_f32 v12, v9, v21, v12 op_sel:[0,1,0] op_sel_hi:[0,1,0]
	v_fma_mix_f32 v102, v6, v112, v180 op_sel_hi:[0,1,0]
	v_fma_mix_f32 v102, v7, v112, v102 op_sel:[0,1,0] op_sel_hi:[0,1,0]
	v_add_f32_dpp v12, v12, v12 row_ror:1 row_mask:0xf bank_mask:0xf bound_ctrl:1
	v_fma_mix_f32 v102, v8, v113, v102 op_sel_hi:[0,1,0]
	v_fma_mix_f32 v102, v9, v113, v102 op_sel:[0,1,0] op_sel_hi:[0,1,0]
	v_add_f32_dpp v12, v12, v12 row_ror:2 row_mask:0xf bank_mask:0xf bound_ctrl:1
	v_pk_fma_f32 v[48:49], v[28:29], v[70:71], v[6:7] op_sel_hi:[1,0,1]
	v_pk_fma_f32 v[50:51], v[30:31], v[70:71], v[8:9] op_sel_hi:[1,0,1]
	v_add_f32_dpp v12, v12, v12 row_ror:4 row_mask:0xf bank_mask:0xf bound_ctrl:1
	v_cndmask_b32_e64 v65, v63, v62, s[40:41]
	v_cndmask_b32_e64 v62, v62, v63, s[40:41]
	v_add_f32_dpp v12, v12, v12 row_ror:8 row_mask:0xf bank_mask:0xf bound_ctrl:1
	v_pk_fma_f32 v[6:7], v[24:25], v[12:13], v[48:49] op_sel_hi:[1,0,1] neg_lo:[1,0,0] neg_hi:[1,0,0]
	v_pk_fma_f32 v[8:9], v[26:27], v[12:13], v[50:51] op_sel_hi:[1,0,1] neg_lo:[1,0,0] neg_hi:[1,0,0]
	ds_read_b128 v[110:113], v10 offset:15616
	ds_read_b128 v[106:109], v10 offset:15360
	ds_read_b128 v[118:121], v10 offset:16128
	ds_read_b128 v[114:117], v10 offset:15872
	ds_read_b128 v[66:69], v11 offset:1024
	v_fma_mix_f32 v12, v6, v36, v180 op_sel_hi:[0,1,0]
	v_fma_mix_f32 v12, v7, v36, v12 op_sel:[0,1,0] op_sel_hi:[0,1,0]
	v_fma_mix_f32 v12, v8, v37, v12 op_sel_hi:[0,1,0]
	v_fma_mix_f32 v12, v9, v37, v12 op_sel:[0,1,0] op_sel_hi:[0,1,0]
	v_fma_mix_f32 v103, v6, v22, v180 op_sel_hi:[0,1,0]
	v_fma_mix_f32 v103, v7, v22, v103 op_sel:[0,1,0] op_sel_hi:[0,1,0]
	v_add_f32_dpp v12, v12, v12 row_ror:1 row_mask:0xf bank_mask:0xf bound_ctrl:1
	v_fma_mix_f32 v103, v8, v23, v103 op_sel_hi:[0,1,0]
	v_fma_mix_f32 v103, v9, v23, v103 op_sel:[0,1,0] op_sel_hi:[0,1,0]
	v_add_f32_dpp v12, v12, v12 row_ror:2 row_mask:0xf bank_mask:0xf bound_ctrl:1
	v_pk_fma_f32 v[48:49], v[44:45], v[70:71], v[6:7] op_sel:[0,1,0]
	v_pk_fma_f32 v[50:51], v[46:47], v[70:71], v[8:9] op_sel:[0,1,0]
	v_add_f32_dpp v12, v12, v12 row_ror:4 row_mask:0xf bank_mask:0xf bound_ctrl:1
	v_add_f32_dpp v62, v62, v65 quad_perm:[1,0,3,2] row_mask:0xf bank_mask:0xf bound_ctrl:1
	v_cvt_pk_bf16_f32 v62, v62, v62
	v_add_f32_dpp v12, v12, v12 row_ror:8 row_mask:0xf bank_mask:0xf bound_ctrl:1
	v_pk_fma_f32 v[6:7], v[40:41], v[12:13], v[48:49] op_sel_hi:[1,0,1] neg_lo:[1,0,0] neg_hi:[1,0,0]
	v_pk_fma_f32 v[8:9], v[42:43], v[12:13], v[50:51] op_sel_hi:[1,0,1] neg_lo:[1,0,0] neg_hi:[1,0,0]
	s_waitcnt lgkmcnt(1)
	s_nop 0
	ds_read_b128 v[20:23], v10 offset:16640
	ds_read_b128 v[28:31], v10 offset:17152
	ds_read_b128 v[24:27], v10 offset:16896
	v_fma_mix_f32 v12, v6, v88, v180 op_sel_hi:[0,1,0]
	v_fma_mix_f32 v12, v7, v88, v12 op_sel:[0,1,0] op_sel_hi:[0,1,0]
	v_fma_mix_f32 v12, v8, v89, v12 op_sel_hi:[0,1,0]
	v_fma_mix_f32 v12, v9, v89, v12 op_sel:[0,1,0] op_sel_hi:[0,1,0]
	v_fma_mix_f32 v104, v6, v38, v180 op_sel_hi:[0,1,0]
	v_fma_mix_f32 v104, v7, v38, v104 op_sel:[0,1,0] op_sel_hi:[0,1,0]
	v_add_f32_dpp v12, v12, v12 row_ror:1 row_mask:0xf bank_mask:0xf bound_ctrl:1
	v_fma_mix_f32 v104, v8, v39, v104 op_sel_hi:[0,1,0]
	v_fma_mix_f32 v104, v9, v39, v104 op_sel:[0,1,0] op_sel_hi:[0,1,0]
	v_add_f32_dpp v12, v12, v12 row_ror:2 row_mask:0xf bank_mask:0xf bound_ctrl:1
	v_pk_fma_f32 v[48:49], v[96:97], v[72:73], v[6:7] op_sel_hi:[1,0,1]
	v_pk_fma_f32 v[50:51], v[98:99], v[72:73], v[8:9] op_sel_hi:[1,0,1]
	v_add_f32_dpp v12, v12, v12 row_ror:4 row_mask:0xf bank_mask:0xf bound_ctrl:1
	s_mov_b64 exec, s[100:101]
	s_nop 0
	global_store_short v[170:171], v62, off
	s_mov_b64 exec, -1
	s_nop 0
	v_add_f32_dpp v12, v12, v12 row_ror:8 row_mask:0xf bank_mask:0xf bound_ctrl:1
	v_pk_fma_f32 v[6:7], v[92:93], v[12:13], v[48:49] op_sel_hi:[1,0,1] neg_lo:[1,0,0] neg_hi:[1,0,0]
	v_pk_fma_f32 v[8:9], v[94:95], v[12:13], v[50:51] op_sel_hi:[1,0,1] neg_lo:[1,0,0] neg_hi:[1,0,0]
	ds_read_b128 v[36:39], v10 offset:17664
	ds_read_b128 v[44:47], v10 offset:18176
	ds_read_b128 v[40:43], v10 offset:17920
	v_fma_mix_f32 v12, v6, v110, v180 op_sel_hi:[0,1,0]
	v_fma_mix_f32 v12, v7, v110, v12 op_sel:[0,1,0] op_sel_hi:[0,1,0]
	v_fma_mix_f32 v12, v8, v111, v12 op_sel_hi:[0,1,0]
	v_fma_mix_f32 v12, v9, v111, v12 op_sel:[0,1,0] op_sel_hi:[0,1,0]
	v_fma_mix_f32 v105, v6, v90, v180 op_sel_hi:[0,1,0]
	v_fma_mix_f32 v105, v7, v90, v105 op_sel:[0,1,0] op_sel_hi:[0,1,0]
	v_add_f32_dpp v12, v12, v12 row_ror:1 row_mask:0xf bank_mask:0xf bound_ctrl:1
	v_fma_mix_f32 v105, v8, v91, v105 op_sel_hi:[0,1,0]
	v_fma_mix_f32 v105, v9, v91, v105 op_sel:[0,1,0] op_sel_hi:[0,1,0]
	v_add_f32_dpp v12, v12, v12 row_ror:2 row_mask:0xf bank_mask:0xf bound_ctrl:1
	v_pk_fma_f32 v[48:49], v[118:119], v[72:73], v[6:7] op_sel:[0,1,0]
	v_pk_fma_f32 v[50:51], v[120:121], v[72:73], v[8:9] op_sel:[0,1,0]
	v_add_f32_dpp v12, v12, v12 row_ror:4 row_mask:0xf bank_mask:0xf bound_ctrl:1
	s_nop 1
	s_nop 0
	v_add_f32_dpp v12, v12, v12 row_ror:8 row_mask:0xf bank_mask:0xf bound_ctrl:1
	v_pk_fma_f32 v[6:7], v[114:115], v[12:13], v[48:49] op_sel_hi:[1,0,1] neg_lo:[1,0,0] neg_hi:[1,0,0]
	v_pk_fma_f32 v[8:9], v[116:117], v[12:13], v[50:51] op_sel_hi:[1,0,1] neg_lo:[1,0,0] neg_hi:[1,0,0]
	v_pk_mul_f32 v[6:7], v[6:7], v[106:107]
	v_pk_mul_f32 v[8:9], v[8:9], v[108:109]
	s_waitcnt lgkmcnt(0)
	s_nop 0
	ds_read_b128 v[88:91], v10 offset:18688
	ds_read_b128 v[96:99], v10 offset:19200
	ds_read_b128 v[92:95], v10 offset:18944
	v_fma_mix_f32 v12, v6, v20, v180 op_sel_hi:[0,1,0]
	v_fma_mix_f32 v12, v7, v20, v12 op_sel:[0,1,0] op_sel_hi:[0,1,0]
	v_fma_mix_f32 v12, v8, v21, v12 op_sel_hi:[0,1,0]
	v_fma_mix_f32 v12, v9, v21, v12 op_sel:[0,1,0] op_sel_hi:[0,1,0]
	v_fma_mix_f32 v61, v6, v112, v180 op_sel_hi:[0,1,0]
	v_fma_mix_f32 v61, v7, v112, v61 op_sel:[0,1,0] op_sel_hi:[0,1,0]
	v_add_f32_dpp v12, v12, v12 row_ror:1 row_mask:0xf bank_mask:0xf bound_ctrl:1
	v_fma_mix_f32 v61, v8, v113, v61 op_sel_hi:[0,1,0]
	v_fma_mix_f32 v61, v9, v113, v61 op_sel:[0,1,0] op_sel_hi:[0,1,0]
	v_add_f32_dpp v12, v12, v12 row_ror:2 row_mask:0xf bank_mask:0xf bound_ctrl:1
	v_pk_fma_f32 v[48:49], v[28:29], v[66:67], v[6:7] op_sel_hi:[1,0,1]
	v_pk_fma_f32 v[50:51], v[30:31], v[66:67], v[8:9] op_sel_hi:[1,0,1]
	v_add_f32_dpp v12, v12, v12 row_ror:4 row_mask:0xf bank_mask:0xf bound_ctrl:1
	s_nop 1
	s_nop 0
	v_add_f32_dpp v12, v12, v12 row_ror:8 row_mask:0xf bank_mask:0xf bound_ctrl:1
	v_pk_fma_f32 v[6:7], v[24:25], v[12:13], v[48:49] op_sel_hi:[1,0,1] neg_lo:[1,0,0] neg_hi:[1,0,0]
	v_pk_fma_f32 v[8:9], v[26:27], v[12:13], v[50:51] op_sel_hi:[1,0,1] neg_lo:[1,0,0] neg_hi:[1,0,0]
	ds_read_b128 v[110:113], v10 offset:19712
	ds_read_b128 v[106:109], v10 offset:19456
	ds_read_b128 v[118:121], v10 offset:20224
	ds_read_b128 v[114:117], v10 offset:19968
	ds_read_b128 v[70:73], v11 offset:1280
	v_fma_mix_f32 v12, v6, v36, v180 op_sel_hi:[0,1,0]
	v_fma_mix_f32 v12, v7, v36, v12 op_sel:[0,1,0] op_sel_hi:[0,1,0]
	v_fma_mix_f32 v12, v8, v37, v12 op_sel_hi:[0,1,0]
	v_fma_mix_f32 v12, v9, v37, v12 op_sel:[0,1,0] op_sel_hi:[0,1,0]
	v_fma_mix_f32 v122, v6, v22, v180 op_sel_hi:[0,1,0]
	v_fma_mix_f32 v122, v7, v22, v122 op_sel:[0,1,0] op_sel_hi:[0,1,0]
	v_add_f32_dpp v12, v12, v12 row_ror:1 row_mask:0xf bank_mask:0xf bound_ctrl:1
	v_fma_mix_f32 v122, v8, v23, v122 op_sel_hi:[0,1,0]
	v_fma_mix_f32 v122, v9, v23, v122 op_sel:[0,1,0] op_sel_hi:[0,1,0]
	v_add_f32_dpp v12, v12, v12 row_ror:2 row_mask:0xf bank_mask:0xf bound_ctrl:1
	v_pk_fma_f32 v[48:49], v[44:45], v[66:67], v[6:7] op_sel:[0,1,0]
	v_pk_fma_f32 v[50:51], v[46:47], v[66:67], v[8:9] op_sel:[0,1,0]
	v_add_f32_dpp v12, v12, v12 row_ror:4 row_mask:0xf bank_mask:0xf bound_ctrl:1
	v_add_f32_dpp v83, v83, v83 row_ror:8 row_mask:0xf bank_mask:0xc
	v_add_f32_dpp v83, v52, v52 row_ror:8 row_mask:0xf bank_mask:0x3
	v_add_f32_dpp v100, v100, v100 row_ror:8 row_mask:0xf bank_mask:0xc
	v_add_f32_dpp v12, v12, v12 row_ror:8 row_mask:0xf bank_mask:0xf bound_ctrl:1
	v_pk_fma_f32 v[6:7], v[40:41], v[12:13], v[48:49] op_sel_hi:[1,0,1] neg_lo:[1,0,0] neg_hi:[1,0,0]
	v_pk_fma_f32 v[8:9], v[42:43], v[12:13], v[50:51] op_sel_hi:[1,0,1] neg_lo:[1,0,0] neg_hi:[1,0,0]
	s_waitcnt lgkmcnt(1)
	s_nop 0
	ds_read_b128 v[20:23], v10 offset:20736
	ds_read_b128 v[28:31], v10 offset:21248
	ds_read_b128 v[24:27], v10 offset:20992
	v_fma_mix_f32 v12, v6, v88, v180 op_sel_hi:[0,1,0]
	v_fma_mix_f32 v12, v7, v88, v12 op_sel:[0,1,0] op_sel_hi:[0,1,0]
	v_fma_mix_f32 v12, v8, v89, v12 op_sel_hi:[0,1,0]
	v_fma_mix_f32 v12, v9, v89, v12 op_sel:[0,1,0] op_sel_hi:[0,1,0]
	v_fma_mix_f32 v123, v6, v38, v180 op_sel_hi:[0,1,0]
	v_fma_mix_f32 v123, v7, v38, v123 op_sel:[0,1,0] op_sel_hi:[0,1,0]
	v_add_f32_dpp v12, v12, v12 row_ror:1 row_mask:0xf bank_mask:0xf bound_ctrl:1
	v_fma_mix_f32 v123, v8, v39, v123 op_sel_hi:[0,1,0]
	v_fma_mix_f32 v123, v9, v39, v123 op_sel:[0,1,0] op_sel_hi:[0,1,0]
	v_add_f32_dpp v12, v12, v12 row_ror:2 row_mask:0xf bank_mask:0xf bound_ctrl:1
	v_pk_fma_f32 v[48:49], v[96:97], v[68:69], v[6:7] op_sel_hi:[1,0,1]
	v_pk_fma_f32 v[50:51], v[98:99], v[68:69], v[8:9] op_sel_hi:[1,0,1]
	v_add_f32_dpp v12, v12, v12 row_ror:4 row_mask:0xf bank_mask:0xf bound_ctrl:1
	v_add_f32_dpp v100, v53, v53 row_ror:8 row_mask:0xf bank_mask:0x3
	v_add_f32_dpp v101, v101, v101 row_ror:8 row_mask:0xf bank_mask:0xc
	v_add_f32_dpp v101, v54, v54 row_ror:8 row_mask:0xf bank_mask:0x3
	v_add_f32_dpp v12, v12, v12 row_ror:8 row_mask:0xf bank_mask:0xf bound_ctrl:1
	v_pk_fma_f32 v[6:7], v[92:93], v[12:13], v[48:49] op_sel_hi:[1,0,1] neg_lo:[1,0,0] neg_hi:[1,0,0]
	v_pk_fma_f32 v[8:9], v[94:95], v[12:13], v[50:51] op_sel_hi:[1,0,1] neg_lo:[1,0,0] neg_hi:[1,0,0]
	ds_read_b128 v[36:39], v10 offset:21760
	ds_read_b128 v[44:47], v10 offset:22272
	ds_read_b128 v[40:43], v10 offset:22016
	v_fma_mix_f32 v12, v6, v110, v180 op_sel_hi:[0,1,0]
	v_fma_mix_f32 v12, v7, v110, v12 op_sel:[0,1,0] op_sel_hi:[0,1,0]
	v_fma_mix_f32 v12, v8, v111, v12 op_sel_hi:[0,1,0]
	v_fma_mix_f32 v12, v9, v111, v12 op_sel:[0,1,0] op_sel_hi:[0,1,0]
	v_fma_mix_f32 v124, v6, v90, v180 op_sel_hi:[0,1,0]
	v_fma_mix_f32 v124, v7, v90, v124 op_sel:[0,1,0] op_sel_hi:[0,1,0]
	v_add_f32_dpp v12, v12, v12 row_ror:1 row_mask:0xf bank_mask:0xf bound_ctrl:1
	v_fma_mix_f32 v124, v8, v91, v124 op_sel_hi:[0,1,0]
	v_fma_mix_f32 v124, v9, v91, v124 op_sel:[0,1,0] op_sel_hi:[0,1,0]
	v_add_f32_dpp v12, v12, v12 row_ror:2 row_mask:0xf bank_mask:0xf bound_ctrl:1
	v_pk_fma_f32 v[48:49], v[118:119], v[68:69], v[6:7] op_sel:[0,1,0]
	v_pk_fma_f32 v[50:51], v[120:121], v[68:69], v[8:9] op_sel:[0,1,0]
	v_add_f32_dpp v12, v12, v12 row_ror:4 row_mask:0xf bank_mask:0xf bound_ctrl:1
	v_add_f32_dpp v102, v102, v102 row_ror:8 row_mask:0xf bank_mask:0xc
	v_add_f32_dpp v102, v55, v55 row_ror:8 row_mask:0xf bank_mask:0x3
	v_add_f32_dpp v103, v103, v103 row_ror:8 row_mask:0xf bank_mask:0xc
	v_add_f32_dpp v12, v12, v12 row_ror:8 row_mask:0xf bank_mask:0xf bound_ctrl:1
	v_pk_fma_f32 v[6:7], v[114:115], v[12:13], v[48:49] op_sel_hi:[1,0,1] neg_lo:[1,0,0] neg_hi:[1,0,0]
	v_pk_fma_f32 v[8:9], v[116:117], v[12:13], v[50:51] op_sel_hi:[1,0,1] neg_lo:[1,0,0] neg_hi:[1,0,0]
	v_pk_mul_f32 v[6:7], v[6:7], v[106:107]
	v_pk_mul_f32 v[8:9], v[8:9], v[108:109]
	s_waitcnt lgkmcnt(0)
	s_nop 0
	ds_read_b128 v[88:91], v10 offset:22784
	ds_read_b128 v[96:99], v10 offset:23296
	ds_read_b128 v[92:95], v10 offset:23040
	v_fma_mix_f32 v12, v6, v20, v180 op_sel_hi:[0,1,0]
	v_fma_mix_f32 v12, v7, v20, v12 op_sel:[0,1,0] op_sel_hi:[0,1,0]
	v_fma_mix_f32 v12, v8, v21, v12 op_sel_hi:[0,1,0]
	v_fma_mix_f32 v12, v9, v21, v12 op_sel:[0,1,0] op_sel_hi:[0,1,0]
	v_fma_mix_f32 v125, v6, v112, v180 op_sel_hi:[0,1,0]
	v_fma_mix_f32 v125, v7, v112, v125 op_sel:[0,1,0] op_sel_hi:[0,1,0]
	v_add_f32_dpp v12, v12, v12 row_ror:1 row_mask:0xf bank_mask:0xf bound_ctrl:1
	v_fma_mix_f32 v125, v8, v113, v125 op_sel_hi:[0,1,0]
	v_fma_mix_f32 v125, v9, v113, v125 op_sel:[0,1,0] op_sel_hi:[0,1,0]
	v_add_f32_dpp v12, v12, v12 row_ror:2 row_mask:0xf bank_mask:0xf bound_ctrl:1
	v_pk_fma_f32 v[48:49], v[28:29], v[70:71], v[6:7] op_sel_hi:[1,0,1]
	v_pk_fma_f32 v[50:51], v[30:31], v[70:71], v[8:9] op_sel_hi:[1,0,1]
	v_add_f32_dpp v12, v12, v12 row_ror:4 row_mask:0xf bank_mask:0xf bound_ctrl:1
	v_add_f32_dpp v103, v56, v56 row_ror:8 row_mask:0xf bank_mask:0x3
	v_add_f32_dpp v104, v104, v104 row_ror:8 row_mask:0xf bank_mask:0xc
	v_add_f32_dpp v104, v57, v57 row_ror:8 row_mask:0xf bank_mask:0x3
	v_add_f32_dpp v12, v12, v12 row_ror:8 row_mask:0xf bank_mask:0xf bound_ctrl:1
	v_pk_fma_f32 v[6:7], v[24:25], v[12:13], v[48:49] op_sel_hi:[1,0,1] neg_lo:[1,0,0] neg_hi:[1,0,0]
	v_pk_fma_f32 v[8:9], v[26:27], v[12:13], v[50:51] op_sel_hi:[1,0,1] neg_lo:[1,0,0] neg_hi:[1,0,0]
	ds_read_b128 v[110:113], v10 offset:23808
	ds_read_b128 v[106:109], v10 offset:23552
	ds_read_b128 v[118:121], v10 offset:24320
	ds_read_b128 v[114:117], v10 offset:24064
	ds_read_b128 v[66:69], v11 offset:1536
	v_fma_mix_f32 v12, v6, v36, v180 op_sel_hi:[0,1,0]
	v_fma_mix_f32 v12, v7, v36, v12 op_sel:[0,1,0] op_sel_hi:[0,1,0]
	v_fma_mix_f32 v12, v8, v37, v12 op_sel_hi:[0,1,0]
	v_fma_mix_f32 v12, v9, v37, v12 op_sel:[0,1,0] op_sel_hi:[0,1,0]
	v_fma_mix_f32 v126, v6, v22, v180 op_sel_hi:[0,1,0]
	v_fma_mix_f32 v126, v7, v22, v126 op_sel:[0,1,0] op_sel_hi:[0,1,0]
	v_add_f32_dpp v12, v12, v12 row_ror:1 row_mask:0xf bank_mask:0xf bound_ctrl:1
	v_fma_mix_f32 v126, v8, v23, v126 op_sel_hi:[0,1,0]
	v_fma_mix_f32 v126, v9, v23, v126 op_sel:[0,1,0] op_sel_hi:[0,1,0]
	v_add_f32_dpp v12, v12, v12 row_ror:2 row_mask:0xf bank_mask:0xf bound_ctrl:1
	v_pk_fma_f32 v[48:49], v[44:45], v[70:71], v[6:7] op_sel:[0,1,0]
	v_pk_fma_f32 v[50:51], v[46:47], v[70:71], v[8:9] op_sel:[0,1,0]
	v_add_f32_dpp v12, v12, v12 row_ror:4 row_mask:0xf bank_mask:0xf bound_ctrl:1
	v_add_f32_dpp v105, v105, v105 row_ror:8 row_mask:0xf bank_mask:0xc
	v_add_f32_dpp v105, v81, v81 row_ror:8 row_mask:0xf bank_mask:0x3
	v_add_f32_dpp v12, v12, v12 row_ror:8 row_mask:0xf bank_mask:0xf bound_ctrl:1
	v_pk_fma_f32 v[6:7], v[40:41], v[12:13], v[48:49] op_sel_hi:[1,0,1] neg_lo:[1,0,0] neg_hi:[1,0,0]
	v_pk_fma_f32 v[8:9], v[42:43], v[12:13], v[50:51] op_sel_hi:[1,0,1] neg_lo:[1,0,0] neg_hi:[1,0,0]
	s_waitcnt lgkmcnt(1)
	s_nop 0
	ds_read_b128 v[20:23], v10 offset:24832
	ds_read_b128 v[28:31], v10 offset:25344
	ds_read_b128 v[24:27], v10 offset:25088
	v_fma_mix_f32 v12, v6, v88, v180 op_sel_hi:[0,1,0]
	v_fma_mix_f32 v12, v7, v88, v12 op_sel:[0,1,0] op_sel_hi:[0,1,0]
	v_fma_mix_f32 v12, v8, v89, v12 op_sel_hi:[0,1,0]
	v_fma_mix_f32 v12, v9, v89, v12 op_sel:[0,1,0] op_sel_hi:[0,1,0]
	v_fma_mix_f32 v127, v6, v38, v180 op_sel_hi:[0,1,0]
	v_fma_mix_f32 v127, v7, v38, v127 op_sel:[0,1,0] op_sel_hi:[0,1,0]
	v_add_f32_dpp v12, v12, v12 row_ror:1 row_mask:0xf bank_mask:0xf bound_ctrl:1
	v_fma_mix_f32 v127, v8, v39, v127 op_sel_hi:[0,1,0]
	v_fma_mix_f32 v127, v9, v39, v127 op_sel:[0,1,0] op_sel_hi:[0,1,0]
	v_add_f32_dpp v12, v12, v12 row_ror:2 row_mask:0xf bank_mask:0xf bound_ctrl:1
	v_pk_fma_f32 v[48:49], v[96:97], v[72:73], v[6:7] op_sel_hi:[1,0,1]
	v_pk_fma_f32 v[50:51], v[98:99], v[72:73], v[8:9] op_sel_hi:[1,0,1]
	v_add_f32_dpp v12, v12, v12 row_ror:4 row_mask:0xf bank_mask:0xf bound_ctrl:1
	v_add_f32_dpp v61, v61, v61 row_ror:8 row_mask:0xf bank_mask:0xc
	v_add_f32_dpp v61, v82, v82 row_ror:8 row_mask:0xf bank_mask:0x3
	v_add_f32_dpp v12, v12, v12 row_ror:8 row_mask:0xf bank_mask:0xf bound_ctrl:1
	v_pk_fma_f32 v[6:7], v[92:93], v[12:13], v[48:49] op_sel_hi:[1,0,1] neg_lo:[1,0,0] neg_hi:[1,0,0]
	v_pk_fma_f32 v[8:9], v[94:95], v[12:13], v[50:51] op_sel_hi:[1,0,1] neg_lo:[1,0,0] neg_hi:[1,0,0]
	ds_read_b128 v[36:39], v10 offset:25856
	ds_read_b128 v[44:47], v10 offset:26368
	ds_read_b128 v[40:43], v10 offset:26112
	v_fma_mix_f32 v12, v6, v110, v180 op_sel_hi:[0,1,0]
	v_fma_mix_f32 v12, v7, v110, v12 op_sel:[0,1,0] op_sel_hi:[0,1,0]
	v_fma_mix_f32 v12, v8, v111, v12 op_sel_hi:[0,1,0]
	v_fma_mix_f32 v12, v9, v111, v12 op_sel:[0,1,0] op_sel_hi:[0,1,0]
	v_fma_mix_f32 v128, v6, v90, v180 op_sel_hi:[0,1,0]
	v_fma_mix_f32 v128, v7, v90, v128 op_sel:[0,1,0] op_sel_hi:[0,1,0]
	v_add_f32_dpp v12, v12, v12 row_ror:1 row_mask:0xf bank_mask:0xf bound_ctrl:1
	v_fma_mix_f32 v128, v8, v91, v128 op_sel_hi:[0,1,0]
	v_fma_mix_f32 v128, v9, v91, v128 op_sel:[0,1,0] op_sel_hi:[0,1,0]
	v_add_f32_dpp v12, v12, v12 row_ror:2 row_mask:0xf bank_mask:0xf bound_ctrl:1
	v_pk_fma_f32 v[48:49], v[118:119], v[72:73], v[6:7] op_sel:[0,1,0]
	v_pk_fma_f32 v[50:51], v[120:121], v[72:73], v[8:9] op_sel:[0,1,0]
	v_add_f32_dpp v12, v12, v12 row_ror:4 row_mask:0xf bank_mask:0xf bound_ctrl:1
	v_add_f32_dpp v103, v103, v103 row_ror:4 row_mask:0xf bank_mask:0xa
	v_add_f32_dpp v103, v83, v83 row_ror:12 row_mask:0xf bank_mask:0x5
	v_add_f32_dpp v104, v104, v104 row_ror:4 row_mask:0xf bank_mask:0xa
	v_add_f32_dpp v12, v12, v12 row_ror:8 row_mask:0xf bank_mask:0xf bound_ctrl:1
	v_pk_fma_f32 v[6:7], v[114:115], v[12:13], v[48:49] op_sel_hi:[1,0,1] neg_lo:[1,0,0] neg_hi:[1,0,0]
	v_pk_fma_f32 v[8:9], v[116:117], v[12:13], v[50:51] op_sel_hi:[1,0,1] neg_lo:[1,0,0] neg_hi:[1,0,0]
	v_pk_mul_f32 v[6:7], v[6:7], v[106:107]
	v_pk_mul_f32 v[8:9], v[8:9], v[108:109]
	s_waitcnt lgkmcnt(0)
	s_nop 0
	ds_read_b128 v[88:91], v10 offset:26880
	ds_read_b128 v[96:99], v10 offset:27392
	ds_read_b128 v[92:95], v10 offset:27136
	v_fma_mix_f32 v12, v6, v20, v180 op_sel_hi:[0,1,0]
	v_fma_mix_f32 v12, v7, v20, v12 op_sel:[0,1,0] op_sel_hi:[0,1,0]
	v_fma_mix_f32 v12, v8, v21, v12 op_sel_hi:[0,1,0]
	v_fma_mix_f32 v12, v9, v21, v12 op_sel:[0,1,0] op_sel_hi:[0,1,0]
	v_fma_mix_f32 v129, v6, v112, v180 op_sel_hi:[0,1,0]
	v_fma_mix_f32 v129, v7, v112, v129 op_sel:[0,1,0] op_sel_hi:[0,1,0]
	v_add_f32_dpp v12, v12, v12 row_ror:1 row_mask:0xf bank_mask:0xf bound_ctrl:1
	v_fma_mix_f32 v129, v8, v113, v129 op_sel_hi:[0,1,0]
	v_fma_mix_f32 v129, v9, v113, v129 op_sel:[0,1,0] op_sel_hi:[0,1,0]
	v_add_f32_dpp v12, v12, v12 row_ror:2 row_mask:0xf bank_mask:0xf bound_ctrl:1
	v_pk_fma_f32 v[48:49], v[28:29], v[66:67], v[6:7] op_sel_hi:[1,0,1]
	v_pk_fma_f32 v[50:51], v[30:31], v[66:67], v[8:9] op_sel_hi:[1,0,1]
	v_add_f32_dpp v12, v12, v12 row_ror:4 row_mask:0xf bank_mask:0xf bound_ctrl:1
	v_add_f32_dpp v104, v100, v100 row_ror:12 row_mask:0xf bank_mask:0x5
	v_add_f32_dpp v105, v105, v105 row_ror:4 row_mask:0xf bank_mask:0xa
	v_add_f32_dpp v105, v101, v101 row_ror:12 row_mask:0xf bank_mask:0x5
	v_add_f32_dpp v12, v12, v12 row_ror:8 row_mask:0xf bank_mask:0xf bound_ctrl:1
	v_pk_fma_f32 v[6:7], v[24:25], v[12:13], v[48:49] op_sel_hi:[1,0,1] neg_lo:[1,0,0] neg_hi:[1,0,0]
	v_pk_fma_f32 v[8:9], v[26:27], v[12:13], v[50:51] op_sel_hi:[1,0,1] neg_lo:[1,0,0] neg_hi:[1,0,0]
	ds_read_b128 v[110:113], v10 offset:27904
	ds_read_b128 v[106:109], v10 offset:27648
	ds_read_b128 v[118:121], v10 offset:28416
	ds_read_b128 v[114:117], v10 offset:28160
	ds_read_b128 v[70:73], v11 offset:1792
	v_fma_mix_f32 v12, v6, v36, v180 op_sel_hi:[0,1,0]
	v_fma_mix_f32 v12, v7, v36, v12 op_sel:[0,1,0] op_sel_hi:[0,1,0]
	v_fma_mix_f32 v12, v8, v37, v12 op_sel_hi:[0,1,0]
	v_fma_mix_f32 v12, v9, v37, v12 op_sel:[0,1,0] op_sel_hi:[0,1,0]
	v_fma_mix_f32 v130, v6, v22, v180 op_sel_hi:[0,1,0]
	v_fma_mix_f32 v130, v7, v22, v130 op_sel:[0,1,0] op_sel_hi:[0,1,0]
	v_add_f32_dpp v12, v12, v12 row_ror:1 row_mask:0xf bank_mask:0xf bound_ctrl:1
	v_fma_mix_f32 v130, v8, v23, v130 op_sel_hi:[0,1,0]
	v_fma_mix_f32 v130, v9, v23, v130 op_sel:[0,1,0] op_sel_hi:[0,1,0]
	v_add_f32_dpp v12, v12, v12 row_ror:2 row_mask:0xf bank_mask:0xf bound_ctrl:1
	v_pk_fma_f32 v[48:49], v[44:45], v[66:67], v[6:7] op_sel:[0,1,0]
	v_pk_fma_f32 v[50:51], v[46:47], v[66:67], v[8:9] op_sel:[0,1,0]
	v_add_f32_dpp v12, v12, v12 row_ror:4 row_mask:0xf bank_mask:0xf bound_ctrl:1
	v_add_f32_dpp v61, v61, v61 row_ror:4 row_mask:0xf bank_mask:0xa
	v_add_f32_dpp v61, v102, v102 row_ror:12 row_mask:0xf bank_mask:0x5
	v_add_f32_dpp v12, v12, v12 row_ror:8 row_mask:0xf bank_mask:0xf bound_ctrl:1
	v_pk_fma_f32 v[6:7], v[40:41], v[12:13], v[48:49] op_sel_hi:[1,0,1] neg_lo:[1,0,0] neg_hi:[1,0,0]
	v_pk_fma_f32 v[8:9], v[42:43], v[12:13], v[50:51] op_sel_hi:[1,0,1] neg_lo:[1,0,0] neg_hi:[1,0,0]
	s_waitcnt lgkmcnt(1)
	s_nop 0
	ds_read_b128 v[20:23], v10 offset:28928
	ds_read_b128 v[28:31], v10 offset:29440
	ds_read_b128 v[24:27], v10 offset:29184
	v_fma_mix_f32 v12, v6, v88, v180 op_sel_hi:[0,1,0]
	v_fma_mix_f32 v12, v7, v88, v12 op_sel:[0,1,0] op_sel_hi:[0,1,0]
	v_fma_mix_f32 v12, v8, v89, v12 op_sel_hi:[0,1,0]
	v_fma_mix_f32 v12, v9, v89, v12 op_sel:[0,1,0] op_sel_hi:[0,1,0]
	v_fma_mix_f32 v131, v6, v38, v180 op_sel_hi:[0,1,0]
	v_fma_mix_f32 v131, v7, v38, v131 op_sel:[0,1,0] op_sel_hi:[0,1,0]
	v_add_f32_dpp v12, v12, v12 row_ror:1 row_mask:0xf bank_mask:0xf bound_ctrl:1
	v_fma_mix_f32 v131, v8, v39, v131 op_sel_hi:[0,1,0]
	v_fma_mix_f32 v131, v9, v39, v131 op_sel:[0,1,0] op_sel_hi:[0,1,0]
	v_add_f32_dpp v12, v12, v12 row_ror:2 row_mask:0xf bank_mask:0xf bound_ctrl:1
	v_pk_fma_f32 v[48:49], v[96:97], v[68:69], v[6:7] op_sel_hi:[1,0,1]
	v_pk_fma_f32 v[50:51], v[98:99], v[68:69], v[8:9] op_sel_hi:[1,0,1]
	v_add_f32_dpp v12, v12, v12 row_ror:4 row_mask:0xf bank_mask:0xf bound_ctrl:1
	v_cndmask_b32_e64 v62, v105, v103, s[38:39]
	v_cndmask_b32_e64 v63, v103, v105, s[38:39]
	v_add_f32_dpp v12, v12, v12 row_ror:8 row_mask:0xf bank_mask:0xf bound_ctrl:1
	v_pk_fma_f32 v[6:7], v[92:93], v[12:13], v[48:49] op_sel_hi:[1,0,1] neg_lo:[1,0,0] neg_hi:[1,0,0]
	v_pk_fma_f32 v[8:9], v[94:95], v[12:13], v[50:51] op_sel_hi:[1,0,1] neg_lo:[1,0,0] neg_hi:[1,0,0]
	ds_read_b128 v[36:39], v10 offset:29952
	ds_read_b128 v[44:47], v10 offset:30464
	ds_read_b128 v[40:43], v10 offset:30208
	v_fma_mix_f32 v12, v6, v110, v180 op_sel_hi:[0,1,0]
	v_fma_mix_f32 v12, v7, v110, v12 op_sel:[0,1,0] op_sel_hi:[0,1,0]
	v_fma_mix_f32 v12, v8, v111, v12 op_sel_hi:[0,1,0]
	v_fma_mix_f32 v12, v9, v111, v12 op_sel:[0,1,0] op_sel_hi:[0,1,0]
	v_fma_mix_f32 v132, v6, v90, v180 op_sel_hi:[0,1,0]
	v_fma_mix_f32 v132, v7, v90, v132 op_sel:[0,1,0] op_sel_hi:[0,1,0]
	v_add_f32_dpp v12, v12, v12 row_ror:1 row_mask:0xf bank_mask:0xf bound_ctrl:1
	v_fma_mix_f32 v132, v8, v91, v132 op_sel_hi:[0,1,0]
	v_fma_mix_f32 v132, v9, v91, v132 op_sel:[0,1,0] op_sel_hi:[0,1,0]
	v_add_f32_dpp v12, v12, v12 row_ror:2 row_mask:0xf bank_mask:0xf bound_ctrl:1
	v_pk_fma_f32 v[48:49], v[118:119], v[68:69], v[6:7] op_sel:[0,1,0]
	v_pk_fma_f32 v[50:51], v[120:121], v[68:69], v[8:9] op_sel:[0,1,0]
	v_add_f32_dpp v12, v12, v12 row_ror:4 row_mask:0xf bank_mask:0xf bound_ctrl:1
	v_cndmask_b32_e64 v64, v61, v104, s[38:39]
	v_cndmask_b32_e64 v65, v104, v61, s[38:39]
	v_add_f32_dpp v12, v12, v12 row_ror:8 row_mask:0xf bank_mask:0xf bound_ctrl:1
	v_pk_fma_f32 v[6:7], v[114:115], v[12:13], v[48:49] op_sel_hi:[1,0,1] neg_lo:[1,0,0] neg_hi:[1,0,0]
	v_pk_fma_f32 v[8:9], v[116:117], v[12:13], v[50:51] op_sel_hi:[1,0,1] neg_lo:[1,0,0] neg_hi:[1,0,0]
	v_pk_mul_f32 v[6:7], v[6:7], v[106:107]
	v_pk_mul_f32 v[8:9], v[8:9], v[108:109]
	s_waitcnt lgkmcnt(0)
	s_nop 0
	ds_read_b128 v[88:91], v10 offset:30976
	ds_read_b128 v[96:99], v10 offset:31488
	ds_read_b128 v[92:95], v10 offset:31232
	v_fma_mix_f32 v12, v6, v20, v180 op_sel_hi:[0,1,0]
	v_fma_mix_f32 v12, v7, v20, v12 op_sel:[0,1,0] op_sel_hi:[0,1,0]
	v_fma_mix_f32 v12, v8, v21, v12 op_sel_hi:[0,1,0]
	v_fma_mix_f32 v12, v9, v21, v12 op_sel:[0,1,0] op_sel_hi:[0,1,0]
	v_fma_mix_f32 v133, v6, v112, v180 op_sel_hi:[0,1,0]
	v_fma_mix_f32 v133, v7, v112, v133 op_sel:[0,1,0] op_sel_hi:[0,1,0]
	v_add_f32_dpp v12, v12, v12 row_ror:1 row_mask:0xf bank_mask:0xf bound_ctrl:1
	v_fma_mix_f32 v133, v8, v113, v133 op_sel_hi:[0,1,0]
	v_fma_mix_f32 v133, v9, v113, v133 op_sel:[0,1,0] op_sel_hi:[0,1,0]
	v_add_f32_dpp v12, v12, v12 row_ror:2 row_mask:0xf bank_mask:0xf bound_ctrl:1
	v_pk_fma_f32 v[48:49], v[28:29], v[70:71], v[6:7] op_sel_hi:[1,0,1]
	v_pk_fma_f32 v[50:51], v[30:31], v[70:71], v[8:9] op_sel_hi:[1,0,1]
	v_add_f32_dpp v12, v12, v12 row_ror:4 row_mask:0xf bank_mask:0xf bound_ctrl:1
	v_add_f32_dpp v62, v63, v62 quad_perm:[2,3,0,1] row_mask:0xf bank_mask:0xf bound_ctrl:1
	v_add_f32_dpp v63, v65, v64 quad_perm:[2,3,0,1] row_mask:0xf bank_mask:0xf bound_ctrl:1
	v_add_f32_dpp v12, v12, v12 row_ror:8 row_mask:0xf bank_mask:0xf bound_ctrl:1
	v_pk_fma_f32 v[6:7], v[24:25], v[12:13], v[48:49] op_sel_hi:[1,0,1] neg_lo:[1,0,0] neg_hi:[1,0,0]
	v_pk_fma_f32 v[8:9], v[26:27], v[12:13], v[50:51] op_sel_hi:[1,0,1] neg_lo:[1,0,0] neg_hi:[1,0,0]
	ds_read_b128 v[110:113], v10 offset:32000
	ds_read_b128 v[106:109], v10 offset:31744
	ds_read_b128 v[118:121], v10 offset:32512
	ds_read_b128 v[114:117], v10 offset:32256
	ds_read_b128 v[66:69], v11 offset:2048
	v_fma_mix_f32 v12, v6, v36, v180 op_sel_hi:[0,1,0]
	v_fma_mix_f32 v12, v7, v36, v12 op_sel:[0,1,0] op_sel_hi:[0,1,0]
	v_fma_mix_f32 v12, v8, v37, v12 op_sel_hi:[0,1,0]
	v_fma_mix_f32 v12, v9, v37, v12 op_sel:[0,1,0] op_sel_hi:[0,1,0]
	v_fma_mix_f32 v134, v6, v22, v180 op_sel_hi:[0,1,0]
	v_fma_mix_f32 v134, v7, v22, v134 op_sel:[0,1,0] op_sel_hi:[0,1,0]
	v_add_f32_dpp v12, v12, v12 row_ror:1 row_mask:0xf bank_mask:0xf bound_ctrl:1
	v_fma_mix_f32 v134, v8, v23, v134 op_sel_hi:[0,1,0]
	v_fma_mix_f32 v134, v9, v23, v134 op_sel:[0,1,0] op_sel_hi:[0,1,0]
	v_add_f32_dpp v12, v12, v12 row_ror:2 row_mask:0xf bank_mask:0xf bound_ctrl:1
	v_pk_fma_f32 v[48:49], v[44:45], v[70:71], v[6:7] op_sel:[0,1,0]
	v_pk_fma_f32 v[50:51], v[46:47], v[70:71], v[8:9] op_sel:[0,1,0]
	v_add_f32_dpp v12, v12, v12 row_ror:4 row_mask:0xf bank_mask:0xf bound_ctrl:1
	v_cndmask_b32_e64 v65, v63, v62, s[40:41]
	v_cndmask_b32_e64 v62, v62, v63, s[40:41]
	v_add_f32_dpp v12, v12, v12 row_ror:8 row_mask:0xf bank_mask:0xf bound_ctrl:1
	v_pk_fma_f32 v[6:7], v[40:41], v[12:13], v[48:49] op_sel_hi:[1,0,1] neg_lo:[1,0,0] neg_hi:[1,0,0]
	v_pk_fma_f32 v[8:9], v[42:43], v[12:13], v[50:51] op_sel_hi:[1,0,1] neg_lo:[1,0,0] neg_hi:[1,0,0]
	s_waitcnt lgkmcnt(1)
	s_nop 0
	ds_read_b128 v[20:23], v10 offset:33024
	ds_read_b128 v[28:31], v10 offset:33536
	ds_read_b128 v[24:27], v10 offset:33280
	v_fma_mix_f32 v12, v6, v88, v180 op_sel_hi:[0,1,0]
	v_fma_mix_f32 v12, v7, v88, v12 op_sel:[0,1,0] op_sel_hi:[0,1,0]
	v_fma_mix_f32 v12, v8, v89, v12 op_sel_hi:[0,1,0]
	v_fma_mix_f32 v12, v9, v89, v12 op_sel:[0,1,0] op_sel_hi:[0,1,0]
	v_fma_mix_f32 v135, v6, v38, v180 op_sel_hi:[0,1,0]
	v_fma_mix_f32 v135, v7, v38, v135 op_sel:[0,1,0] op_sel_hi:[0,1,0]
	v_add_f32_dpp v12, v12, v12 row_ror:1 row_mask:0xf bank_mask:0xf bound_ctrl:1
	v_fma_mix_f32 v135, v8, v39, v135 op_sel_hi:[0,1,0]
	v_fma_mix_f32 v135, v9, v39, v135 op_sel:[0,1,0] op_sel_hi:[0,1,0]
	v_add_f32_dpp v12, v12, v12 row_ror:2 row_mask:0xf bank_mask:0xf bound_ctrl:1
	v_pk_fma_f32 v[48:49], v[96:97], v[72:73], v[6:7] op_sel_hi:[1,0,1]
	v_pk_fma_f32 v[50:51], v[98:99], v[72:73], v[8:9] op_sel_hi:[1,0,1]
	v_add_f32_dpp v12, v12, v12 row_ror:4 row_mask:0xf bank_mask:0xf bound_ctrl:1
	v_add_f32_dpp v62, v62, v65 quad_perm:[1,0,3,2] row_mask:0xf bank_mask:0xf bound_ctrl:1
	v_cvt_pk_bf16_f32 v62, v62, v62
	v_add_f32_dpp v12, v12, v12 row_ror:8 row_mask:0xf bank_mask:0xf bound_ctrl:1
	v_pk_fma_f32 v[6:7], v[92:93], v[12:13], v[48:49] op_sel_hi:[1,0,1] neg_lo:[1,0,0] neg_hi:[1,0,0]
	v_pk_fma_f32 v[8:9], v[94:95], v[12:13], v[50:51] op_sel_hi:[1,0,1] neg_lo:[1,0,0] neg_hi:[1,0,0]
	ds_read_b128 v[36:39], v10 offset:34048
	ds_read_b128 v[44:47], v10 offset:34560
	ds_read_b128 v[40:43], v10 offset:34304
	v_fma_mix_f32 v12, v6, v110, v180 op_sel_hi:[0,1,0]
	v_fma_mix_f32 v12, v7, v110, v12 op_sel:[0,1,0] op_sel_hi:[0,1,0]
	v_fma_mix_f32 v12, v8, v111, v12 op_sel_hi:[0,1,0]
	v_fma_mix_f32 v12, v9, v111, v12 op_sel:[0,1,0] op_sel_hi:[0,1,0]
	v_fma_mix_f32 v136, v6, v90, v180 op_sel_hi:[0,1,0]
	v_fma_mix_f32 v136, v7, v90, v136 op_sel:[0,1,0] op_sel_hi:[0,1,0]
	v_add_f32_dpp v12, v12, v12 row_ror:1 row_mask:0xf bank_mask:0xf bound_ctrl:1
	v_fma_mix_f32 v136, v8, v91, v136 op_sel_hi:[0,1,0]
	v_fma_mix_f32 v136, v9, v91, v136 op_sel:[0,1,0] op_sel_hi:[0,1,0]
	v_add_f32_dpp v12, v12, v12 row_ror:2 row_mask:0xf bank_mask:0xf bound_ctrl:1
	v_pk_fma_f32 v[48:49], v[118:119], v[72:73], v[6:7] op_sel:[0,1,0]
	v_pk_fma_f32 v[50:51], v[120:121], v[72:73], v[8:9] op_sel:[0,1,0]
	v_add_f32_dpp v12, v12, v12 row_ror:4 row_mask:0xf bank_mask:0xf bound_ctrl:1
	global_store_short v[2:3], v62, off
	v_lshl_add_u64 v[2:3], v[2:3], 0, s[84:85]
	v_add_f32_dpp v12, v12, v12 row_ror:8 row_mask:0xf bank_mask:0xf bound_ctrl:1
	v_pk_fma_f32 v[6:7], v[114:115], v[12:13], v[48:49] op_sel_hi:[1,0,1] neg_lo:[1,0,0] neg_hi:[1,0,0]
	v_pk_fma_f32 v[8:9], v[116:117], v[12:13], v[50:51] op_sel_hi:[1,0,1] neg_lo:[1,0,0] neg_hi:[1,0,0]
	v_pk_mul_f32 v[6:7], v[6:7], v[106:107]
	v_pk_mul_f32 v[8:9], v[8:9], v[108:109]
	s_waitcnt lgkmcnt(0)
	s_nop 0
	ds_read_b128 v[88:91], v10 offset:35072
	ds_read_b128 v[96:99], v10 offset:35584
	ds_read_b128 v[92:95], v10 offset:35328
	v_fma_mix_f32 v12, v6, v20, v180 op_sel_hi:[0,1,0]
	v_fma_mix_f32 v12, v7, v20, v12 op_sel:[0,1,0] op_sel_hi:[0,1,0]
	v_fma_mix_f32 v12, v8, v21, v12 op_sel_hi:[0,1,0]
	v_fma_mix_f32 v12, v9, v21, v12 op_sel:[0,1,0] op_sel_hi:[0,1,0]
	v_fma_mix_f32 v137, v6, v112, v180 op_sel_hi:[0,1,0]
	v_fma_mix_f32 v137, v7, v112, v137 op_sel:[0,1,0] op_sel_hi:[0,1,0]
	v_add_f32_dpp v12, v12, v12 row_ror:1 row_mask:0xf bank_mask:0xf bound_ctrl:1
	v_fma_mix_f32 v137, v8, v113, v137 op_sel_hi:[0,1,0]
	v_fma_mix_f32 v137, v9, v113, v137 op_sel:[0,1,0] op_sel_hi:[0,1,0]
	v_add_f32_dpp v12, v12, v12 row_ror:2 row_mask:0xf bank_mask:0xf bound_ctrl:1
	v_pk_fma_f32 v[48:49], v[28:29], v[66:67], v[6:7] op_sel_hi:[1,0,1]
	v_pk_fma_f32 v[50:51], v[30:31], v[66:67], v[8:9] op_sel_hi:[1,0,1]
	v_add_f32_dpp v12, v12, v12 row_ror:4 row_mask:0xf bank_mask:0xf bound_ctrl:1
	s_nop 1
	s_nop 0
	v_add_f32_dpp v12, v12, v12 row_ror:8 row_mask:0xf bank_mask:0xf bound_ctrl:1
	v_pk_fma_f32 v[6:7], v[24:25], v[12:13], v[48:49] op_sel_hi:[1,0,1] neg_lo:[1,0,0] neg_hi:[1,0,0]
	v_pk_fma_f32 v[8:9], v[26:27], v[12:13], v[50:51] op_sel_hi:[1,0,1] neg_lo:[1,0,0] neg_hi:[1,0,0]
	ds_read_b128 v[110:113], v10 offset:36096
	ds_read_b128 v[106:109], v10 offset:35840
	ds_read_b128 v[118:121], v10 offset:36608
	ds_read_b128 v[114:117], v10 offset:36352
	ds_read_b128 v[70:73], v11 offset:2304
	v_fma_mix_f32 v12, v6, v36, v180 op_sel_hi:[0,1,0]
	v_fma_mix_f32 v12, v7, v36, v12 op_sel:[0,1,0] op_sel_hi:[0,1,0]
	v_fma_mix_f32 v12, v8, v37, v12 op_sel_hi:[0,1,0]
	v_fma_mix_f32 v12, v9, v37, v12 op_sel:[0,1,0] op_sel_hi:[0,1,0]
	v_fma_mix_f32 v52, v6, v22, v180 op_sel_hi:[0,1,0]
	v_fma_mix_f32 v52, v7, v22, v52 op_sel:[0,1,0] op_sel_hi:[0,1,0]
	v_add_f32_dpp v12, v12, v12 row_ror:1 row_mask:0xf bank_mask:0xf bound_ctrl:1
	v_fma_mix_f32 v52, v8, v23, v52 op_sel_hi:[0,1,0]
	v_fma_mix_f32 v52, v9, v23, v52 op_sel:[0,1,0] op_sel_hi:[0,1,0]
	v_add_f32_dpp v12, v12, v12 row_ror:2 row_mask:0xf bank_mask:0xf bound_ctrl:1
	v_pk_fma_f32 v[48:49], v[44:45], v[66:67], v[6:7] op_sel:[0,1,0]
	v_pk_fma_f32 v[50:51], v[46:47], v[66:67], v[8:9] op_sel:[0,1,0]
	v_add_f32_dpp v12, v12, v12 row_ror:4 row_mask:0xf bank_mask:0xf bound_ctrl:1
	v_add_f32_dpp v130, v130, v130 row_ror:8 row_mask:0xf bank_mask:0xc
	v_add_f32_dpp v130, v122, v122 row_ror:8 row_mask:0xf bank_mask:0x3
	v_add_f32_dpp v131, v131, v131 row_ror:8 row_mask:0xf bank_mask:0xc
	v_add_f32_dpp v12, v12, v12 row_ror:8 row_mask:0xf bank_mask:0xf bound_ctrl:1
	v_pk_fma_f32 v[6:7], v[40:41], v[12:13], v[48:49] op_sel_hi:[1,0,1] neg_lo:[1,0,0] neg_hi:[1,0,0]
	v_pk_fma_f32 v[8:9], v[42:43], v[12:13], v[50:51] op_sel_hi:[1,0,1] neg_lo:[1,0,0] neg_hi:[1,0,0]
	s_waitcnt lgkmcnt(1)
	s_nop 0
	ds_read_b128 v[20:23], v10 offset:37120
	ds_read_b128 v[28:31], v10 offset:37632
	ds_read_b128 v[24:27], v10 offset:37376
	v_fma_mix_f32 v12, v6, v88, v180 op_sel_hi:[0,1,0]
	v_fma_mix_f32 v12, v7, v88, v12 op_sel:[0,1,0] op_sel_hi:[0,1,0]
	v_fma_mix_f32 v12, v8, v89, v12 op_sel_hi:[0,1,0]
	v_fma_mix_f32 v12, v9, v89, v12 op_sel:[0,1,0] op_sel_hi:[0,1,0]
	v_fma_mix_f32 v53, v6, v38, v180 op_sel_hi:[0,1,0]
	v_fma_mix_f32 v53, v7, v38, v53 op_sel:[0,1,0] op_sel_hi:[0,1,0]
	v_add_f32_dpp v12, v12, v12 row_ror:1 row_mask:0xf bank_mask:0xf bound_ctrl:1
	v_fma_mix_f32 v53, v8, v39, v53 op_sel_hi:[0,1,0]
	v_fma_mix_f32 v53, v9, v39, v53 op_sel:[0,1,0] op_sel_hi:[0,1,0]
	v_add_f32_dpp v12, v12, v12 row_ror:2 row_mask:0xf bank_mask:0xf bound_ctrl:1
	v_pk_fma_f32 v[48:49], v[96:97], v[68:69], v[6:7] op_sel_hi:[1,0,1]
	v_pk_fma_f32 v[50:51], v[98:99], v[68:69], v[8:9] op_sel_hi:[1,0,1]
	v_add_f32_dpp v12, v12, v12 row_ror:4 row_mask:0xf bank_mask:0xf bound_ctrl:1
	v_add_f32_dpp v131, v123, v123 row_ror:8 row_mask:0xf bank_mask:0x3
	v_add_f32_dpp v132, v132, v132 row_ror:8 row_mask:0xf bank_mask:0xc
	v_add_f32_dpp v132, v124, v124 row_ror:8 row_mask:0xf bank_mask:0x3
	v_add_f32_dpp v12, v12, v12 row_ror:8 row_mask:0xf bank_mask:0xf bound_ctrl:1
	v_pk_fma_f32 v[6:7], v[92:93], v[12:13], v[48:49] op_sel_hi:[1,0,1] neg_lo:[1,0,0] neg_hi:[1,0,0]
	v_pk_fma_f32 v[8:9], v[94:95], v[12:13], v[50:51] op_sel_hi:[1,0,1] neg_lo:[1,0,0] neg_hi:[1,0,0]
	ds_read_b128 v[36:39], v10 offset:38144
	ds_read_b128 v[44:47], v10 offset:38656
	ds_read_b128 v[40:43], v10 offset:38400
	v_fma_mix_f32 v12, v6, v110, v180 op_sel_hi:[0,1,0]
	v_fma_mix_f32 v12, v7, v110, v12 op_sel:[0,1,0] op_sel_hi:[0,1,0]
	v_fma_mix_f32 v12, v8, v111, v12 op_sel_hi:[0,1,0]
	v_fma_mix_f32 v12, v9, v111, v12 op_sel:[0,1,0] op_sel_hi:[0,1,0]
	v_fma_mix_f32 v54, v6, v90, v180 op_sel_hi:[0,1,0]
	v_fma_mix_f32 v54, v7, v90, v54 op_sel:[0,1,0] op_sel_hi:[0,1,0]
	v_add_f32_dpp v12, v12, v12 row_ror:1 row_mask:0xf bank_mask:0xf bound_ctrl:1
	v_fma_mix_f32 v54, v8, v91, v54 op_sel_hi:[0,1,0]
	v_fma_mix_f32 v54, v9, v91, v54 op_sel:[0,1,0] op_sel_hi:[0,1,0]
	v_add_f32_dpp v12, v12, v12 row_ror:2 row_mask:0xf bank_mask:0xf bound_ctrl:1
	v_pk_fma_f32 v[48:49], v[118:119], v[68:69], v[6:7] op_sel:[0,1,0]
	v_pk_fma_f32 v[50:51], v[120:121], v[68:69], v[8:9] op_sel:[0,1,0]
	v_add_f32_dpp v12, v12, v12 row_ror:4 row_mask:0xf bank_mask:0xf bound_ctrl:1
	v_add_f32_dpp v133, v133, v133 row_ror:8 row_mask:0xf bank_mask:0xc
	v_add_f32_dpp v133, v125, v125 row_ror:8 row_mask:0xf bank_mask:0x3
	v_add_f32_dpp v134, v134, v134 row_ror:8 row_mask:0xf bank_mask:0xc
	v_add_f32_dpp v12, v12, v12 row_ror:8 row_mask:0xf bank_mask:0xf bound_ctrl:1
	v_pk_fma_f32 v[6:7], v[114:115], v[12:13], v[48:49] op_sel_hi:[1,0,1] neg_lo:[1,0,0] neg_hi:[1,0,0]
	v_pk_fma_f32 v[8:9], v[116:117], v[12:13], v[50:51] op_sel_hi:[1,0,1] neg_lo:[1,0,0] neg_hi:[1,0,0]
	v_pk_mul_f32 v[6:7], v[6:7], v[106:107]
	v_pk_mul_f32 v[8:9], v[8:9], v[108:109]
	s_waitcnt lgkmcnt(0)
	s_nop 0
	ds_read_b128 v[88:91], v10 offset:39168
	ds_read_b128 v[96:99], v10 offset:39680
	ds_read_b128 v[92:95], v10 offset:39424
	v_fma_mix_f32 v12, v6, v20, v180 op_sel_hi:[0,1,0]
	v_fma_mix_f32 v12, v7, v20, v12 op_sel:[0,1,0] op_sel_hi:[0,1,0]
	v_fma_mix_f32 v12, v8, v21, v12 op_sel_hi:[0,1,0]
	v_fma_mix_f32 v12, v9, v21, v12 op_sel:[0,1,0] op_sel_hi:[0,1,0]
	v_fma_mix_f32 v55, v6, v112, v180 op_sel_hi:[0,1,0]
	v_fma_mix_f32 v55, v7, v112, v55 op_sel:[0,1,0] op_sel_hi:[0,1,0]
	v_add_f32_dpp v12, v12, v12 row_ror:1 row_mask:0xf bank_mask:0xf bound_ctrl:1
	v_fma_mix_f32 v55, v8, v113, v55 op_sel_hi:[0,1,0]
	v_fma_mix_f32 v55, v9, v113, v55 op_sel:[0,1,0] op_sel_hi:[0,1,0]
	v_add_f32_dpp v12, v12, v12 row_ror:2 row_mask:0xf bank_mask:0xf bound_ctrl:1
	v_pk_fma_f32 v[48:49], v[28:29], v[70:71], v[6:7] op_sel_hi:[1,0,1]
	v_pk_fma_f32 v[50:51], v[30:31], v[70:71], v[8:9] op_sel_hi:[1,0,1]
	v_add_f32_dpp v12, v12, v12 row_ror:4 row_mask:0xf bank_mask:0xf bound_ctrl:1
	v_add_f32_dpp v134, v126, v126 row_ror:8 row_mask:0xf bank_mask:0x3
	v_add_f32_dpp v135, v135, v135 row_ror:8 row_mask:0xf bank_mask:0xc
	v_add_f32_dpp v135, v127, v127 row_ror:8 row_mask:0xf bank_mask:0x3
	v_add_f32_dpp v12, v12, v12 row_ror:8 row_mask:0xf bank_mask:0xf bound_ctrl:1
	v_pk_fma_f32 v[6:7], v[24:25], v[12:13], v[48:49] op_sel_hi:[1,0,1] neg_lo:[1,0,0] neg_hi:[1,0,0]
	v_pk_fma_f32 v[8:9], v[26:27], v[12:13], v[50:51] op_sel_hi:[1,0,1] neg_lo:[1,0,0] neg_hi:[1,0,0]
	ds_read_b128 v[110:113], v10 offset:40192
	ds_read_b128 v[106:109], v10 offset:39936
	ds_read_b128 v[118:121], v10 offset:40704
	ds_read_b128 v[114:117], v10 offset:40448
	ds_read_b128 v[66:69], v11 offset:2560
	v_fma_mix_f32 v12, v6, v36, v180 op_sel_hi:[0,1,0]
	v_fma_mix_f32 v12, v7, v36, v12 op_sel:[0,1,0] op_sel_hi:[0,1,0]
	v_fma_mix_f32 v12, v8, v37, v12 op_sel_hi:[0,1,0]
	v_fma_mix_f32 v12, v9, v37, v12 op_sel:[0,1,0] op_sel_hi:[0,1,0]
	v_fma_mix_f32 v56, v6, v22, v180 op_sel_hi:[0,1,0]
	v_fma_mix_f32 v56, v7, v22, v56 op_sel:[0,1,0] op_sel_hi:[0,1,0]
	v_add_f32_dpp v12, v12, v12 row_ror:1 row_mask:0xf bank_mask:0xf bound_ctrl:1
	v_fma_mix_f32 v56, v8, v23, v56 op_sel_hi:[0,1,0]
	v_fma_mix_f32 v56, v9, v23, v56 op_sel:[0,1,0] op_sel_hi:[0,1,0]
	v_add_f32_dpp v12, v12, v12 row_ror:2 row_mask:0xf bank_mask:0xf bound_ctrl:1
	v_pk_fma_f32 v[48:49], v[44:45], v[70:71], v[6:7] op_sel:[0,1,0]
	v_pk_fma_f32 v[50:51], v[46:47], v[70:71], v[8:9] op_sel:[0,1,0]
	v_add_f32_dpp v12, v12, v12 row_ror:4 row_mask:0xf bank_mask:0xf bound_ctrl:1
	v_add_f32_dpp v136, v136, v136 row_ror:8 row_mask:0xf bank_mask:0xc
	v_add_f32_dpp v136, v128, v128 row_ror:8 row_mask:0xf bank_mask:0x3
	v_add_f32_dpp v12, v12, v12 row_ror:8 row_mask:0xf bank_mask:0xf bound_ctrl:1
	v_pk_fma_f32 v[6:7], v[40:41], v[12:13], v[48:49] op_sel_hi:[1,0,1] neg_lo:[1,0,0] neg_hi:[1,0,0]
	v_pk_fma_f32 v[8:9], v[42:43], v[12:13], v[50:51] op_sel_hi:[1,0,1] neg_lo:[1,0,0] neg_hi:[1,0,0]
	s_waitcnt lgkmcnt(1)
	s_nop 0
	ds_read_b128 v[20:23], v10 offset:41216
	ds_read_b128 v[28:31], v10 offset:41728
	ds_read_b128 v[24:27], v10 offset:41472
	v_fma_mix_f32 v12, v6, v88, v180 op_sel_hi:[0,1,0]
	v_fma_mix_f32 v12, v7, v88, v12 op_sel:[0,1,0] op_sel_hi:[0,1,0]
	v_fma_mix_f32 v12, v8, v89, v12 op_sel_hi:[0,1,0]
	v_fma_mix_f32 v12, v9, v89, v12 op_sel:[0,1,0] op_sel_hi:[0,1,0]
	v_fma_mix_f32 v57, v6, v38, v180 op_sel_hi:[0,1,0]
	v_fma_mix_f32 v57, v7, v38, v57 op_sel:[0,1,0] op_sel_hi:[0,1,0]
	v_add_f32_dpp v12, v12, v12 row_ror:1 row_mask:0xf bank_mask:0xf bound_ctrl:1
	v_fma_mix_f32 v57, v8, v39, v57 op_sel_hi:[0,1,0]
	v_fma_mix_f32 v57, v9, v39, v57 op_sel:[0,1,0] op_sel_hi:[0,1,0]
	v_add_f32_dpp v12, v12, v12 row_ror:2 row_mask:0xf bank_mask:0xf bound_ctrl:1
	v_pk_fma_f32 v[48:49], v[96:97], v[72:73], v[6:7] op_sel_hi:[1,0,1]
	v_pk_fma_f32 v[50:51], v[98:99], v[72:73], v[8:9] op_sel_hi:[1,0,1]
	v_add_f32_dpp v12, v12, v12 row_ror:4 row_mask:0xf bank_mask:0xf bound_ctrl:1
	v_add_f32_dpp v137, v137, v137 row_ror:8 row_mask:0xf bank_mask:0xc
	v_add_f32_dpp v137, v129, v129 row_ror:8 row_mask:0xf bank_mask:0x3
	v_add_f32_dpp v12, v12, v12 row_ror:8 row_mask:0xf bank_mask:0xf bound_ctrl:1
	v_pk_fma_f32 v[6:7], v[92:93], v[12:13], v[48:49] op_sel_hi:[1,0,1] neg_lo:[1,0,0] neg_hi:[1,0,0]
	v_pk_fma_f32 v[8:9], v[94:95], v[12:13], v[50:51] op_sel_hi:[1,0,1] neg_lo:[1,0,0] neg_hi:[1,0,0]
	ds_read_b128 v[36:39], v10 offset:42240
	ds_read_b128 v[44:47], v10 offset:42752
	ds_read_b128 v[40:43], v10 offset:42496
	v_fma_mix_f32 v12, v6, v110, v180 op_sel_hi:[0,1,0]
	v_fma_mix_f32 v12, v7, v110, v12 op_sel:[0,1,0] op_sel_hi:[0,1,0]
	v_fma_mix_f32 v12, v8, v111, v12 op_sel_hi:[0,1,0]
	v_fma_mix_f32 v12, v9, v111, v12 op_sel:[0,1,0] op_sel_hi:[0,1,0]
	v_fma_mix_f32 v81, v6, v90, v180 op_sel_hi:[0,1,0]
	v_fma_mix_f32 v81, v7, v90, v81 op_sel:[0,1,0] op_sel_hi:[0,1,0]
	v_add_f32_dpp v12, v12, v12 row_ror:1 row_mask:0xf bank_mask:0xf bound_ctrl:1
	v_fma_mix_f32 v81, v8, v91, v81 op_sel_hi:[0,1,0]
	v_fma_mix_f32 v81, v9, v91, v81 op_sel:[0,1,0] op_sel_hi:[0,1,0]
	v_add_f32_dpp v12, v12, v12 row_ror:2 row_mask:0xf bank_mask:0xf bound_ctrl:1
	v_pk_fma_f32 v[48:49], v[118:119], v[72:73], v[6:7] op_sel:[0,1,0]
	v_pk_fma_f32 v[50:51], v[120:121], v[72:73], v[8:9] op_sel:[0,1,0]
	v_add_f32_dpp v12, v12, v12 row_ror:4 row_mask:0xf bank_mask:0xf bound_ctrl:1
	v_add_f32_dpp v134, v134, v134 row_ror:4 row_mask:0xf bank_mask:0xa
	v_add_f32_dpp v134, v130, v130 row_ror:12 row_mask:0xf bank_mask:0x5
	v_add_f32_dpp v135, v135, v135 row_ror:4 row_mask:0xf bank_mask:0xa
	v_add_f32_dpp v12, v12, v12 row_ror:8 row_mask:0xf bank_mask:0xf bound_ctrl:1
	v_pk_fma_f32 v[6:7], v[114:115], v[12:13], v[48:49] op_sel_hi:[1,0,1] neg_lo:[1,0,0] neg_hi:[1,0,0]
	v_pk_fma_f32 v[8:9], v[116:117], v[12:13], v[50:51] op_sel_hi:[1,0,1] neg_lo:[1,0,0] neg_hi:[1,0,0]
	v_pk_mul_f32 v[6:7], v[6:7], v[106:107]
	v_pk_mul_f32 v[8:9], v[8:9], v[108:109]
	s_waitcnt lgkmcnt(0)
	s_nop 0
	ds_read_b128 v[88:91], v10 offset:43264
	ds_read_b128 v[96:99], v10 offset:43776
	ds_read_b128 v[92:95], v10 offset:43520
	v_fma_mix_f32 v12, v6, v20, v180 op_sel_hi:[0,1,0]
	v_fma_mix_f32 v12, v7, v20, v12 op_sel:[0,1,0] op_sel_hi:[0,1,0]
	v_fma_mix_f32 v12, v8, v21, v12 op_sel_hi:[0,1,0]
	v_fma_mix_f32 v12, v9, v21, v12 op_sel:[0,1,0] op_sel_hi:[0,1,0]
	v_fma_mix_f32 v82, v6, v112, v180 op_sel_hi:[0,1,0]
	v_fma_mix_f32 v82, v7, v112, v82 op_sel:[0,1,0] op_sel_hi:[0,1,0]
	v_add_f32_dpp v12, v12, v12 row_ror:1 row_mask:0xf bank_mask:0xf bound_ctrl:1
	v_fma_mix_f32 v82, v8, v113, v82 op_sel_hi:[0,1,0]
	v_fma_mix_f32 v82, v9, v113, v82 op_sel:[0,1,0] op_sel_hi:[0,1,0]
	v_add_f32_dpp v12, v12, v12 row_ror:2 row_mask:0xf bank_mask:0xf bound_ctrl:1
	v_pk_fma_f32 v[48:49], v[28:29], v[66:67], v[6:7] op_sel_hi:[1,0,1]
	v_pk_fma_f32 v[50:51], v[30:31], v[66:67], v[8:9] op_sel_hi:[1,0,1]
	v_add_f32_dpp v12, v12, v12 row_ror:4 row_mask:0xf bank_mask:0xf bound_ctrl:1
	v_add_f32_dpp v135, v131, v131 row_ror:12 row_mask:0xf bank_mask:0x5
	v_add_f32_dpp v136, v136, v136 row_ror:4 row_mask:0xf bank_mask:0xa
	v_add_f32_dpp v136, v132, v132 row_ror:12 row_mask:0xf bank_mask:0x5
	v_add_f32_dpp v12, v12, v12 row_ror:8 row_mask:0xf bank_mask:0xf bound_ctrl:1
	v_pk_fma_f32 v[6:7], v[24:25], v[12:13], v[48:49] op_sel_hi:[1,0,1] neg_lo:[1,0,0] neg_hi:[1,0,0]
	v_pk_fma_f32 v[8:9], v[26:27], v[12:13], v[50:51] op_sel_hi:[1,0,1] neg_lo:[1,0,0] neg_hi:[1,0,0]
	ds_read_b128 v[110:113], v10 offset:44288
	ds_read_b128 v[106:109], v10 offset:44032
	ds_read_b128 v[118:121], v10 offset:44800
	ds_read_b128 v[114:117], v10 offset:44544
	ds_read_b128 v[70:73], v11 offset:2816
	v_fma_mix_f32 v12, v6, v36, v180 op_sel_hi:[0,1,0]
	v_fma_mix_f32 v12, v7, v36, v12 op_sel:[0,1,0] op_sel_hi:[0,1,0]
	v_fma_mix_f32 v12, v8, v37, v12 op_sel_hi:[0,1,0]
	v_fma_mix_f32 v12, v9, v37, v12 op_sel:[0,1,0] op_sel_hi:[0,1,0]
	v_fma_mix_f32 v83, v6, v22, v180 op_sel_hi:[0,1,0]
	v_fma_mix_f32 v83, v7, v22, v83 op_sel:[0,1,0] op_sel_hi:[0,1,0]
	v_add_f32_dpp v12, v12, v12 row_ror:1 row_mask:0xf bank_mask:0xf bound_ctrl:1
	v_fma_mix_f32 v83, v8, v23, v83 op_sel_hi:[0,1,0]
	v_fma_mix_f32 v83, v9, v23, v83 op_sel:[0,1,0] op_sel_hi:[0,1,0]
	v_add_f32_dpp v12, v12, v12 row_ror:2 row_mask:0xf bank_mask:0xf bound_ctrl:1
	v_pk_fma_f32 v[48:49], v[44:45], v[66:67], v[6:7] op_sel:[0,1,0]
	v_pk_fma_f32 v[50:51], v[46:47], v[66:67], v[8:9] op_sel:[0,1,0]
	v_add_f32_dpp v12, v12, v12 row_ror:4 row_mask:0xf bank_mask:0xf bound_ctrl:1
	v_add_f32_dpp v137, v137, v137 row_ror:4 row_mask:0xf bank_mask:0xa
	v_add_f32_dpp v137, v133, v133 row_ror:12 row_mask:0xf bank_mask:0x5
	v_add_f32_dpp v12, v12, v12 row_ror:8 row_mask:0xf bank_mask:0xf bound_ctrl:1
	v_pk_fma_f32 v[6:7], v[40:41], v[12:13], v[48:49] op_sel_hi:[1,0,1] neg_lo:[1,0,0] neg_hi:[1,0,0]
	v_pk_fma_f32 v[8:9], v[42:43], v[12:13], v[50:51] op_sel_hi:[1,0,1] neg_lo:[1,0,0] neg_hi:[1,0,0]
	s_waitcnt lgkmcnt(1)
	s_nop 0
	ds_read_b128 v[20:23], v10 offset:45312
	ds_read_b128 v[28:31], v10 offset:45824
	ds_read_b128 v[24:27], v10 offset:45568
	v_fma_mix_f32 v12, v6, v88, v180 op_sel_hi:[0,1,0]
	v_fma_mix_f32 v12, v7, v88, v12 op_sel:[0,1,0] op_sel_hi:[0,1,0]
	v_fma_mix_f32 v12, v8, v89, v12 op_sel_hi:[0,1,0]
	v_fma_mix_f32 v12, v9, v89, v12 op_sel:[0,1,0] op_sel_hi:[0,1,0]
	v_fma_mix_f32 v100, v6, v38, v180 op_sel_hi:[0,1,0]
	v_fma_mix_f32 v100, v7, v38, v100 op_sel:[0,1,0] op_sel_hi:[0,1,0]
	v_add_f32_dpp v12, v12, v12 row_ror:1 row_mask:0xf bank_mask:0xf bound_ctrl:1
	v_fma_mix_f32 v100, v8, v39, v100 op_sel_hi:[0,1,0]
	v_fma_mix_f32 v100, v9, v39, v100 op_sel:[0,1,0] op_sel_hi:[0,1,0]
	v_add_f32_dpp v12, v12, v12 row_ror:2 row_mask:0xf bank_mask:0xf bound_ctrl:1
	v_pk_fma_f32 v[48:49], v[96:97], v[68:69], v[6:7] op_sel_hi:[1,0,1]
	v_pk_fma_f32 v[50:51], v[98:99], v[68:69], v[8:9] op_sel_hi:[1,0,1]
	v_add_f32_dpp v12, v12, v12 row_ror:4 row_mask:0xf bank_mask:0xf bound_ctrl:1
	v_cndmask_b32_e64 v62, v136, v134, s[38:39]
	v_cndmask_b32_e64 v63, v134, v136, s[38:39]
	v_add_f32_dpp v12, v12, v12 row_ror:8 row_mask:0xf bank_mask:0xf bound_ctrl:1
	v_pk_fma_f32 v[6:7], v[92:93], v[12:13], v[48:49] op_sel_hi:[1,0,1] neg_lo:[1,0,0] neg_hi:[1,0,0]
	v_pk_fma_f32 v[8:9], v[94:95], v[12:13], v[50:51] op_sel_hi:[1,0,1] neg_lo:[1,0,0] neg_hi:[1,0,0]
	ds_read_b128 v[36:39], v10 offset:46336
	ds_read_b128 v[44:47], v10 offset:46848
	ds_read_b128 v[40:43], v10 offset:46592
	v_fma_mix_f32 v12, v6, v110, v180 op_sel_hi:[0,1,0]
	v_fma_mix_f32 v12, v7, v110, v12 op_sel:[0,1,0] op_sel_hi:[0,1,0]
	v_fma_mix_f32 v12, v8, v111, v12 op_sel_hi:[0,1,0]
	v_fma_mix_f32 v12, v9, v111, v12 op_sel:[0,1,0] op_sel_hi:[0,1,0]
	v_fma_mix_f32 v101, v6, v90, v180 op_sel_hi:[0,1,0]
	v_fma_mix_f32 v101, v7, v90, v101 op_sel:[0,1,0] op_sel_hi:[0,1,0]
	v_add_f32_dpp v12, v12, v12 row_ror:1 row_mask:0xf bank_mask:0xf bound_ctrl:1
	v_fma_mix_f32 v101, v8, v91, v101 op_sel_hi:[0,1,0]
	v_fma_mix_f32 v101, v9, v91, v101 op_sel:[0,1,0] op_sel_hi:[0,1,0]
	v_add_f32_dpp v12, v12, v12 row_ror:2 row_mask:0xf bank_mask:0xf bound_ctrl:1
	v_pk_fma_f32 v[48:49], v[118:119], v[68:69], v[6:7] op_sel:[0,1,0]
	v_pk_fma_f32 v[50:51], v[120:121], v[68:69], v[8:9] op_sel:[0,1,0]
	v_add_f32_dpp v12, v12, v12 row_ror:4 row_mask:0xf bank_mask:0xf bound_ctrl:1
	v_cndmask_b32_e64 v64, v137, v135, s[38:39]
	v_cndmask_b32_e64 v65, v135, v137, s[38:39]
	v_add_f32_dpp v12, v12, v12 row_ror:8 row_mask:0xf bank_mask:0xf bound_ctrl:1
	v_pk_fma_f32 v[6:7], v[114:115], v[12:13], v[48:49] op_sel_hi:[1,0,1] neg_lo:[1,0,0] neg_hi:[1,0,0]
	v_pk_fma_f32 v[8:9], v[116:117], v[12:13], v[50:51] op_sel_hi:[1,0,1] neg_lo:[1,0,0] neg_hi:[1,0,0]
	v_pk_mul_f32 v[6:7], v[6:7], v[106:107]
	v_pk_mul_f32 v[8:9], v[8:9], v[108:109]
	s_waitcnt lgkmcnt(0)
	s_nop 0
	ds_read_b128 v[88:91], v10 offset:47360
	ds_read_b128 v[96:99], v10 offset:47872
	ds_read_b128 v[92:95], v10 offset:47616
	v_fma_mix_f32 v12, v6, v20, v180 op_sel_hi:[0,1,0]
	v_fma_mix_f32 v12, v7, v20, v12 op_sel:[0,1,0] op_sel_hi:[0,1,0]
	v_fma_mix_f32 v12, v8, v21, v12 op_sel_hi:[0,1,0]
	v_fma_mix_f32 v12, v9, v21, v12 op_sel:[0,1,0] op_sel_hi:[0,1,0]
	v_fma_mix_f32 v102, v6, v112, v180 op_sel_hi:[0,1,0]
	v_fma_mix_f32 v102, v7, v112, v102 op_sel:[0,1,0] op_sel_hi:[0,1,0]
	v_add_f32_dpp v12, v12, v12 row_ror:1 row_mask:0xf bank_mask:0xf bound_ctrl:1
	v_fma_mix_f32 v102, v8, v113, v102 op_sel_hi:[0,1,0]
	v_fma_mix_f32 v102, v9, v113, v102 op_sel:[0,1,0] op_sel_hi:[0,1,0]
	v_add_f32_dpp v12, v12, v12 row_ror:2 row_mask:0xf bank_mask:0xf bound_ctrl:1
	v_pk_fma_f32 v[48:49], v[28:29], v[70:71], v[6:7] op_sel_hi:[1,0,1]
	v_pk_fma_f32 v[50:51], v[30:31], v[70:71], v[8:9] op_sel_hi:[1,0,1]
	v_add_f32_dpp v12, v12, v12 row_ror:4 row_mask:0xf bank_mask:0xf bound_ctrl:1
	v_add_f32_dpp v62, v63, v62 quad_perm:[2,3,0,1] row_mask:0xf bank_mask:0xf bound_ctrl:1
	v_add_f32_dpp v63, v65, v64 quad_perm:[2,3,0,1] row_mask:0xf bank_mask:0xf bound_ctrl:1
	v_add_f32_dpp v12, v12, v12 row_ror:8 row_mask:0xf bank_mask:0xf bound_ctrl:1
	v_pk_fma_f32 v[6:7], v[24:25], v[12:13], v[48:49] op_sel_hi:[1,0,1] neg_lo:[1,0,0] neg_hi:[1,0,0]
	v_pk_fma_f32 v[8:9], v[26:27], v[12:13], v[50:51] op_sel_hi:[1,0,1] neg_lo:[1,0,0] neg_hi:[1,0,0]
	ds_read_b128 v[110:113], v10 offset:48384
	ds_read_b128 v[106:109], v10 offset:48128
	ds_read_b128 v[118:121], v10 offset:48896
	ds_read_b128 v[114:117], v10 offset:48640
	ds_read_b128 v[66:69], v11 offset:3072
	v_fma_mix_f32 v12, v6, v36, v180 op_sel_hi:[0,1,0]
	v_fma_mix_f32 v12, v7, v36, v12 op_sel:[0,1,0] op_sel_hi:[0,1,0]
	v_fma_mix_f32 v12, v8, v37, v12 op_sel_hi:[0,1,0]
	v_fma_mix_f32 v12, v9, v37, v12 op_sel:[0,1,0] op_sel_hi:[0,1,0]
	v_fma_mix_f32 v103, v6, v22, v180 op_sel_hi:[0,1,0]
	v_fma_mix_f32 v103, v7, v22, v103 op_sel:[0,1,0] op_sel_hi:[0,1,0]
	v_add_f32_dpp v12, v12, v12 row_ror:1 row_mask:0xf bank_mask:0xf bound_ctrl:1
	v_fma_mix_f32 v103, v8, v23, v103 op_sel_hi:[0,1,0]
	v_fma_mix_f32 v103, v9, v23, v103 op_sel:[0,1,0] op_sel_hi:[0,1,0]
	v_add_f32_dpp v12, v12, v12 row_ror:2 row_mask:0xf bank_mask:0xf bound_ctrl:1
	v_pk_fma_f32 v[48:49], v[44:45], v[70:71], v[6:7] op_sel:[0,1,0]
	v_pk_fma_f32 v[50:51], v[46:47], v[70:71], v[8:9] op_sel:[0,1,0]
	v_add_f32_dpp v12, v12, v12 row_ror:4 row_mask:0xf bank_mask:0xf bound_ctrl:1
	v_cndmask_b32_e64 v65, v63, v62, s[40:41]
	v_cndmask_b32_e64 v62, v62, v63, s[40:41]
	v_add_f32_dpp v12, v12, v12 row_ror:8 row_mask:0xf bank_mask:0xf bound_ctrl:1
	v_pk_fma_f32 v[6:7], v[40:41], v[12:13], v[48:49] op_sel_hi:[1,0,1] neg_lo:[1,0,0] neg_hi:[1,0,0]
	v_pk_fma_f32 v[8:9], v[42:43], v[12:13], v[50:51] op_sel_hi:[1,0,1] neg_lo:[1,0,0] neg_hi:[1,0,0]
	s_waitcnt lgkmcnt(1)
	s_nop 0
	ds_read_b128 v[20:23], v10 offset:49408
	ds_read_b128 v[28:31], v10 offset:49920
	ds_read_b128 v[24:27], v10 offset:49664
	v_fma_mix_f32 v12, v6, v88, v180 op_sel_hi:[0,1,0]
	v_fma_mix_f32 v12, v7, v88, v12 op_sel:[0,1,0] op_sel_hi:[0,1,0]
	v_fma_mix_f32 v12, v8, v89, v12 op_sel_hi:[0,1,0]
	v_fma_mix_f32 v12, v9, v89, v12 op_sel:[0,1,0] op_sel_hi:[0,1,0]
	v_fma_mix_f32 v104, v6, v38, v180 op_sel_hi:[0,1,0]
	v_fma_mix_f32 v104, v7, v38, v104 op_sel:[0,1,0] op_sel_hi:[0,1,0]
	v_add_f32_dpp v12, v12, v12 row_ror:1 row_mask:0xf bank_mask:0xf bound_ctrl:1
	v_fma_mix_f32 v104, v8, v39, v104 op_sel_hi:[0,1,0]
	v_fma_mix_f32 v104, v9, v39, v104 op_sel:[0,1,0] op_sel_hi:[0,1,0]
	v_add_f32_dpp v12, v12, v12 row_ror:2 row_mask:0xf bank_mask:0xf bound_ctrl:1
	v_pk_fma_f32 v[48:49], v[96:97], v[72:73], v[6:7] op_sel_hi:[1,0,1]
	v_pk_fma_f32 v[50:51], v[98:99], v[72:73], v[8:9] op_sel_hi:[1,0,1]
	v_add_f32_dpp v12, v12, v12 row_ror:4 row_mask:0xf bank_mask:0xf bound_ctrl:1
	v_add_f32_dpp v62, v62, v65 quad_perm:[1,0,3,2] row_mask:0xf bank_mask:0xf bound_ctrl:1
	v_cvt_pk_bf16_f32 v62, v62, v62
	v_add_f32_dpp v12, v12, v12 row_ror:8 row_mask:0xf bank_mask:0xf bound_ctrl:1
	v_pk_fma_f32 v[6:7], v[92:93], v[12:13], v[48:49] op_sel_hi:[1,0,1] neg_lo:[1,0,0] neg_hi:[1,0,0]
	v_pk_fma_f32 v[8:9], v[94:95], v[12:13], v[50:51] op_sel_hi:[1,0,1] neg_lo:[1,0,0] neg_hi:[1,0,0]
	ds_read_b128 v[36:39], v10 offset:50432
	ds_read_b128 v[44:47], v10 offset:50944
	ds_read_b128 v[40:43], v10 offset:50688
	v_fma_mix_f32 v12, v6, v110, v180 op_sel_hi:[0,1,0]
	v_fma_mix_f32 v12, v7, v110, v12 op_sel:[0,1,0] op_sel_hi:[0,1,0]
	v_fma_mix_f32 v12, v8, v111, v12 op_sel_hi:[0,1,0]
	v_fma_mix_f32 v12, v9, v111, v12 op_sel:[0,1,0] op_sel_hi:[0,1,0]
	v_fma_mix_f32 v105, v6, v90, v180 op_sel_hi:[0,1,0]
	v_fma_mix_f32 v105, v7, v90, v105 op_sel:[0,1,0] op_sel_hi:[0,1,0]
	v_add_f32_dpp v12, v12, v12 row_ror:1 row_mask:0xf bank_mask:0xf bound_ctrl:1
	v_fma_mix_f32 v105, v8, v91, v105 op_sel_hi:[0,1,0]
	v_fma_mix_f32 v105, v9, v91, v105 op_sel:[0,1,0] op_sel_hi:[0,1,0]
	v_add_f32_dpp v12, v12, v12 row_ror:2 row_mask:0xf bank_mask:0xf bound_ctrl:1
	v_pk_fma_f32 v[48:49], v[118:119], v[72:73], v[6:7] op_sel:[0,1,0]
	v_pk_fma_f32 v[50:51], v[120:121], v[72:73], v[8:9] op_sel:[0,1,0]
	v_add_f32_dpp v12, v12, v12 row_ror:4 row_mask:0xf bank_mask:0xf bound_ctrl:1
	global_store_short v[2:3], v62, off
	v_lshl_add_u64 v[2:3], v[2:3], 0, s[84:85]
	v_add_f32_dpp v12, v12, v12 row_ror:8 row_mask:0xf bank_mask:0xf bound_ctrl:1
	v_pk_fma_f32 v[6:7], v[114:115], v[12:13], v[48:49] op_sel_hi:[1,0,1] neg_lo:[1,0,0] neg_hi:[1,0,0]
	v_pk_fma_f32 v[8:9], v[116:117], v[12:13], v[50:51] op_sel_hi:[1,0,1] neg_lo:[1,0,0] neg_hi:[1,0,0]
	v_pk_mul_f32 v[6:7], v[6:7], v[106:107]
	v_pk_mul_f32 v[8:9], v[8:9], v[108:109]
	s_waitcnt lgkmcnt(0)
	s_nop 0
	ds_read_b128 v[88:91], v10 offset:51456
	ds_read_b128 v[96:99], v10 offset:51968
	ds_read_b128 v[92:95], v10 offset:51712
	v_fma_mix_f32 v12, v6, v20, v180 op_sel_hi:[0,1,0]
	v_fma_mix_f32 v12, v7, v20, v12 op_sel:[0,1,0] op_sel_hi:[0,1,0]
	v_fma_mix_f32 v12, v8, v21, v12 op_sel_hi:[0,1,0]
	v_fma_mix_f32 v12, v9, v21, v12 op_sel:[0,1,0] op_sel_hi:[0,1,0]
	v_fma_mix_f32 v61, v6, v112, v180 op_sel_hi:[0,1,0]
	v_fma_mix_f32 v61, v7, v112, v61 op_sel:[0,1,0] op_sel_hi:[0,1,0]
	v_add_f32_dpp v12, v12, v12 row_ror:1 row_mask:0xf bank_mask:0xf bound_ctrl:1
	v_fma_mix_f32 v61, v8, v113, v61 op_sel_hi:[0,1,0]
	v_fma_mix_f32 v61, v9, v113, v61 op_sel:[0,1,0] op_sel_hi:[0,1,0]
	v_add_f32_dpp v12, v12, v12 row_ror:2 row_mask:0xf bank_mask:0xf bound_ctrl:1
	v_pk_fma_f32 v[48:49], v[28:29], v[66:67], v[6:7] op_sel_hi:[1,0,1]
	v_pk_fma_f32 v[50:51], v[30:31], v[66:67], v[8:9] op_sel_hi:[1,0,1]
	v_add_f32_dpp v12, v12, v12 row_ror:4 row_mask:0xf bank_mask:0xf bound_ctrl:1
	s_nop 1
	s_nop 0
	v_add_f32_dpp v12, v12, v12 row_ror:8 row_mask:0xf bank_mask:0xf bound_ctrl:1
	v_pk_fma_f32 v[6:7], v[24:25], v[12:13], v[48:49] op_sel_hi:[1,0,1] neg_lo:[1,0,0] neg_hi:[1,0,0]
	v_pk_fma_f32 v[8:9], v[26:27], v[12:13], v[50:51] op_sel_hi:[1,0,1] neg_lo:[1,0,0] neg_hi:[1,0,0]
	ds_read_b128 v[110:113], v10 offset:52480
	ds_read_b128 v[106:109], v10 offset:52224
	ds_read_b128 v[118:121], v10 offset:52992
	ds_read_b128 v[114:117], v10 offset:52736
	ds_read_b128 v[70:73], v11 offset:3328
	v_fma_mix_f32 v12, v6, v36, v180 op_sel_hi:[0,1,0]
	v_fma_mix_f32 v12, v7, v36, v12 op_sel:[0,1,0] op_sel_hi:[0,1,0]
	v_fma_mix_f32 v12, v8, v37, v12 op_sel_hi:[0,1,0]
	v_fma_mix_f32 v12, v9, v37, v12 op_sel:[0,1,0] op_sel_hi:[0,1,0]
	v_fma_mix_f32 v122, v6, v22, v180 op_sel_hi:[0,1,0]
	v_fma_mix_f32 v122, v7, v22, v122 op_sel:[0,1,0] op_sel_hi:[0,1,0]
	v_add_f32_dpp v12, v12, v12 row_ror:1 row_mask:0xf bank_mask:0xf bound_ctrl:1
	v_fma_mix_f32 v122, v8, v23, v122 op_sel_hi:[0,1,0]
	v_fma_mix_f32 v122, v9, v23, v122 op_sel:[0,1,0] op_sel_hi:[0,1,0]
	v_add_f32_dpp v12, v12, v12 row_ror:2 row_mask:0xf bank_mask:0xf bound_ctrl:1
	v_pk_fma_f32 v[48:49], v[44:45], v[66:67], v[6:7] op_sel:[0,1,0]
	v_pk_fma_f32 v[50:51], v[46:47], v[66:67], v[8:9] op_sel:[0,1,0]
	v_add_f32_dpp v12, v12, v12 row_ror:4 row_mask:0xf bank_mask:0xf bound_ctrl:1
	v_add_f32_dpp v83, v83, v83 row_ror:8 row_mask:0xf bank_mask:0xc
	v_add_f32_dpp v83, v52, v52 row_ror:8 row_mask:0xf bank_mask:0x3
	v_add_f32_dpp v100, v100, v100 row_ror:8 row_mask:0xf bank_mask:0xc
	v_add_f32_dpp v12, v12, v12 row_ror:8 row_mask:0xf bank_mask:0xf bound_ctrl:1
	v_pk_fma_f32 v[6:7], v[40:41], v[12:13], v[48:49] op_sel_hi:[1,0,1] neg_lo:[1,0,0] neg_hi:[1,0,0]
	v_pk_fma_f32 v[8:9], v[42:43], v[12:13], v[50:51] op_sel_hi:[1,0,1] neg_lo:[1,0,0] neg_hi:[1,0,0]
	s_waitcnt lgkmcnt(1)
	s_nop 0
	ds_read_b128 v[20:23], v10 offset:53504
	ds_read_b128 v[28:31], v10 offset:54016
	ds_read_b128 v[24:27], v10 offset:53760
	v_fma_mix_f32 v12, v6, v88, v180 op_sel_hi:[0,1,0]
	v_fma_mix_f32 v12, v7, v88, v12 op_sel:[0,1,0] op_sel_hi:[0,1,0]
	v_fma_mix_f32 v12, v8, v89, v12 op_sel_hi:[0,1,0]
	v_fma_mix_f32 v12, v9, v89, v12 op_sel:[0,1,0] op_sel_hi:[0,1,0]
	v_fma_mix_f32 v123, v6, v38, v180 op_sel_hi:[0,1,0]
	v_fma_mix_f32 v123, v7, v38, v123 op_sel:[0,1,0] op_sel_hi:[0,1,0]
	v_add_f32_dpp v12, v12, v12 row_ror:1 row_mask:0xf bank_mask:0xf bound_ctrl:1
	v_fma_mix_f32 v123, v8, v39, v123 op_sel_hi:[0,1,0]
	v_fma_mix_f32 v123, v9, v39, v123 op_sel:[0,1,0] op_sel_hi:[0,1,0]
	v_add_f32_dpp v12, v12, v12 row_ror:2 row_mask:0xf bank_mask:0xf bound_ctrl:1
	v_pk_fma_f32 v[48:49], v[96:97], v[68:69], v[6:7] op_sel_hi:[1,0,1]
	v_pk_fma_f32 v[50:51], v[98:99], v[68:69], v[8:9] op_sel_hi:[1,0,1]
	v_add_f32_dpp v12, v12, v12 row_ror:4 row_mask:0xf bank_mask:0xf bound_ctrl:1
	v_add_f32_dpp v100, v53, v53 row_ror:8 row_mask:0xf bank_mask:0x3
	v_add_f32_dpp v101, v101, v101 row_ror:8 row_mask:0xf bank_mask:0xc
	v_add_f32_dpp v101, v54, v54 row_ror:8 row_mask:0xf bank_mask:0x3
	v_add_f32_dpp v12, v12, v12 row_ror:8 row_mask:0xf bank_mask:0xf bound_ctrl:1
	v_pk_fma_f32 v[6:7], v[92:93], v[12:13], v[48:49] op_sel_hi:[1,0,1] neg_lo:[1,0,0] neg_hi:[1,0,0]
	v_pk_fma_f32 v[8:9], v[94:95], v[12:13], v[50:51] op_sel_hi:[1,0,1] neg_lo:[1,0,0] neg_hi:[1,0,0]
	ds_read_b128 v[36:39], v10 offset:54528
	ds_read_b128 v[44:47], v10 offset:55040
	ds_read_b128 v[40:43], v10 offset:54784
	v_fma_mix_f32 v12, v6, v110, v180 op_sel_hi:[0,1,0]
	v_fma_mix_f32 v12, v7, v110, v12 op_sel:[0,1,0] op_sel_hi:[0,1,0]
	v_fma_mix_f32 v12, v8, v111, v12 op_sel_hi:[0,1,0]
	v_fma_mix_f32 v12, v9, v111, v12 op_sel:[0,1,0] op_sel_hi:[0,1,0]
	v_fma_mix_f32 v124, v6, v90, v180 op_sel_hi:[0,1,0]
	v_fma_mix_f32 v124, v7, v90, v124 op_sel:[0,1,0] op_sel_hi:[0,1,0]
	v_add_f32_dpp v12, v12, v12 row_ror:1 row_mask:0xf bank_mask:0xf bound_ctrl:1
	v_fma_mix_f32 v124, v8, v91, v124 op_sel_hi:[0,1,0]
	v_fma_mix_f32 v124, v9, v91, v124 op_sel:[0,1,0] op_sel_hi:[0,1,0]
	v_add_f32_dpp v12, v12, v12 row_ror:2 row_mask:0xf bank_mask:0xf bound_ctrl:1
	v_pk_fma_f32 v[48:49], v[118:119], v[68:69], v[6:7] op_sel:[0,1,0]
	v_pk_fma_f32 v[50:51], v[120:121], v[68:69], v[8:9] op_sel:[0,1,0]
	v_add_f32_dpp v12, v12, v12 row_ror:4 row_mask:0xf bank_mask:0xf bound_ctrl:1
	v_add_f32_dpp v102, v102, v102 row_ror:8 row_mask:0xf bank_mask:0xc
	v_add_f32_dpp v102, v55, v55 row_ror:8 row_mask:0xf bank_mask:0x3
	v_add_f32_dpp v103, v103, v103 row_ror:8 row_mask:0xf bank_mask:0xc
	v_add_f32_dpp v12, v12, v12 row_ror:8 row_mask:0xf bank_mask:0xf bound_ctrl:1
	v_pk_fma_f32 v[6:7], v[114:115], v[12:13], v[48:49] op_sel_hi:[1,0,1] neg_lo:[1,0,0] neg_hi:[1,0,0]
	v_pk_fma_f32 v[8:9], v[116:117], v[12:13], v[50:51] op_sel_hi:[1,0,1] neg_lo:[1,0,0] neg_hi:[1,0,0]
	v_pk_mul_f32 v[6:7], v[6:7], v[106:107]
	v_pk_mul_f32 v[8:9], v[8:9], v[108:109]
	s_waitcnt lgkmcnt(0)
	s_nop 0
	ds_read_b128 v[88:91], v10 offset:55552
	ds_read_b128 v[96:99], v10 offset:56064
	ds_read_b128 v[92:95], v10 offset:55808
	v_fma_mix_f32 v12, v6, v20, v180 op_sel_hi:[0,1,0]
	v_fma_mix_f32 v12, v7, v20, v12 op_sel:[0,1,0] op_sel_hi:[0,1,0]
	v_fma_mix_f32 v12, v8, v21, v12 op_sel_hi:[0,1,0]
	v_fma_mix_f32 v12, v9, v21, v12 op_sel:[0,1,0] op_sel_hi:[0,1,0]
	v_fma_mix_f32 v125, v6, v112, v180 op_sel_hi:[0,1,0]
	v_fma_mix_f32 v125, v7, v112, v125 op_sel:[0,1,0] op_sel_hi:[0,1,0]
	v_add_f32_dpp v12, v12, v12 row_ror:1 row_mask:0xf bank_mask:0xf bound_ctrl:1
	v_fma_mix_f32 v125, v8, v113, v125 op_sel_hi:[0,1,0]
	v_fma_mix_f32 v125, v9, v113, v125 op_sel:[0,1,0] op_sel_hi:[0,1,0]
	v_add_f32_dpp v12, v12, v12 row_ror:2 row_mask:0xf bank_mask:0xf bound_ctrl:1
	v_pk_fma_f32 v[48:49], v[28:29], v[70:71], v[6:7] op_sel_hi:[1,0,1]
	v_pk_fma_f32 v[50:51], v[30:31], v[70:71], v[8:9] op_sel_hi:[1,0,1]
	v_add_f32_dpp v12, v12, v12 row_ror:4 row_mask:0xf bank_mask:0xf bound_ctrl:1
	v_add_f32_dpp v103, v56, v56 row_ror:8 row_mask:0xf bank_mask:0x3
	v_add_f32_dpp v104, v104, v104 row_ror:8 row_mask:0xf bank_mask:0xc
	v_add_f32_dpp v104, v57, v57 row_ror:8 row_mask:0xf bank_mask:0x3
	v_add_f32_dpp v12, v12, v12 row_ror:8 row_mask:0xf bank_mask:0xf bound_ctrl:1
	v_pk_fma_f32 v[6:7], v[24:25], v[12:13], v[48:49] op_sel_hi:[1,0,1] neg_lo:[1,0,0] neg_hi:[1,0,0]
	v_pk_fma_f32 v[8:9], v[26:27], v[12:13], v[50:51] op_sel_hi:[1,0,1] neg_lo:[1,0,0] neg_hi:[1,0,0]
	ds_read_b128 v[110:113], v10 offset:56576
	ds_read_b128 v[106:109], v10 offset:56320
	ds_read_b128 v[118:121], v10 offset:57088
	ds_read_b128 v[114:117], v10 offset:56832
	ds_read_b128 v[66:69], v11 offset:3584
	v_fma_mix_f32 v12, v6, v36, v180 op_sel_hi:[0,1,0]
	v_fma_mix_f32 v12, v7, v36, v12 op_sel:[0,1,0] op_sel_hi:[0,1,0]
	v_fma_mix_f32 v12, v8, v37, v12 op_sel_hi:[0,1,0]
	v_fma_mix_f32 v12, v9, v37, v12 op_sel:[0,1,0] op_sel_hi:[0,1,0]
	v_fma_mix_f32 v126, v6, v22, v180 op_sel_hi:[0,1,0]
	v_fma_mix_f32 v126, v7, v22, v126 op_sel:[0,1,0] op_sel_hi:[0,1,0]
	v_add_f32_dpp v12, v12, v12 row_ror:1 row_mask:0xf bank_mask:0xf bound_ctrl:1
	v_fma_mix_f32 v126, v8, v23, v126 op_sel_hi:[0,1,0]
	v_fma_mix_f32 v126, v9, v23, v126 op_sel:[0,1,0] op_sel_hi:[0,1,0]
	v_add_f32_dpp v12, v12, v12 row_ror:2 row_mask:0xf bank_mask:0xf bound_ctrl:1
	v_pk_fma_f32 v[48:49], v[44:45], v[70:71], v[6:7] op_sel:[0,1,0]
	v_pk_fma_f32 v[50:51], v[46:47], v[70:71], v[8:9] op_sel:[0,1,0]
	v_add_f32_dpp v12, v12, v12 row_ror:4 row_mask:0xf bank_mask:0xf bound_ctrl:1
	v_add_f32_dpp v105, v105, v105 row_ror:8 row_mask:0xf bank_mask:0xc
	v_add_f32_dpp v105, v81, v81 row_ror:8 row_mask:0xf bank_mask:0x3
	v_add_f32_dpp v12, v12, v12 row_ror:8 row_mask:0xf bank_mask:0xf bound_ctrl:1
	v_pk_fma_f32 v[6:7], v[40:41], v[12:13], v[48:49] op_sel_hi:[1,0,1] neg_lo:[1,0,0] neg_hi:[1,0,0]
	v_pk_fma_f32 v[8:9], v[42:43], v[12:13], v[50:51] op_sel_hi:[1,0,1] neg_lo:[1,0,0] neg_hi:[1,0,0]
	s_waitcnt lgkmcnt(1)
	s_nop 0
	ds_read_b128 v[20:23], v10 offset:57600
	ds_read_b128 v[28:31], v10 offset:58112
	ds_read_b128 v[24:27], v10 offset:57856
	v_fma_mix_f32 v12, v6, v88, v180 op_sel_hi:[0,1,0]
	v_fma_mix_f32 v12, v7, v88, v12 op_sel:[0,1,0] op_sel_hi:[0,1,0]
	v_fma_mix_f32 v12, v8, v89, v12 op_sel_hi:[0,1,0]
	v_fma_mix_f32 v12, v9, v89, v12 op_sel:[0,1,0] op_sel_hi:[0,1,0]
	v_fma_mix_f32 v127, v6, v38, v180 op_sel_hi:[0,1,0]
	v_fma_mix_f32 v127, v7, v38, v127 op_sel:[0,1,0] op_sel_hi:[0,1,0]
	v_add_f32_dpp v12, v12, v12 row_ror:1 row_mask:0xf bank_mask:0xf bound_ctrl:1
	v_fma_mix_f32 v127, v8, v39, v127 op_sel_hi:[0,1,0]
	v_fma_mix_f32 v127, v9, v39, v127 op_sel:[0,1,0] op_sel_hi:[0,1,0]
	v_add_f32_dpp v12, v12, v12 row_ror:2 row_mask:0xf bank_mask:0xf bound_ctrl:1
	v_pk_fma_f32 v[48:49], v[96:97], v[72:73], v[6:7] op_sel_hi:[1,0,1]
	v_pk_fma_f32 v[50:51], v[98:99], v[72:73], v[8:9] op_sel_hi:[1,0,1]
	v_add_f32_dpp v12, v12, v12 row_ror:4 row_mask:0xf bank_mask:0xf bound_ctrl:1
	v_add_f32_dpp v61, v61, v61 row_ror:8 row_mask:0xf bank_mask:0xc
	v_add_f32_dpp v61, v82, v82 row_ror:8 row_mask:0xf bank_mask:0x3
	v_add_f32_dpp v12, v12, v12 row_ror:8 row_mask:0xf bank_mask:0xf bound_ctrl:1
	v_pk_fma_f32 v[6:7], v[92:93], v[12:13], v[48:49] op_sel_hi:[1,0,1] neg_lo:[1,0,0] neg_hi:[1,0,0]
	v_pk_fma_f32 v[8:9], v[94:95], v[12:13], v[50:51] op_sel_hi:[1,0,1] neg_lo:[1,0,0] neg_hi:[1,0,0]
	ds_read_b128 v[36:39], v10 offset:58624
	ds_read_b128 v[44:47], v10 offset:59136
	ds_read_b128 v[40:43], v10 offset:58880
	v_fma_mix_f32 v12, v6, v110, v180 op_sel_hi:[0,1,0]
	v_fma_mix_f32 v12, v7, v110, v12 op_sel:[0,1,0] op_sel_hi:[0,1,0]
	v_fma_mix_f32 v12, v8, v111, v12 op_sel_hi:[0,1,0]
	v_fma_mix_f32 v12, v9, v111, v12 op_sel:[0,1,0] op_sel_hi:[0,1,0]
	v_fma_mix_f32 v128, v6, v90, v180 op_sel_hi:[0,1,0]
	v_fma_mix_f32 v128, v7, v90, v128 op_sel:[0,1,0] op_sel_hi:[0,1,0]
	v_add_f32_dpp v12, v12, v12 row_ror:1 row_mask:0xf bank_mask:0xf bound_ctrl:1
	v_fma_mix_f32 v128, v8, v91, v128 op_sel_hi:[0,1,0]
	v_fma_mix_f32 v128, v9, v91, v128 op_sel:[0,1,0] op_sel_hi:[0,1,0]
	v_add_f32_dpp v12, v12, v12 row_ror:2 row_mask:0xf bank_mask:0xf bound_ctrl:1
	v_pk_fma_f32 v[48:49], v[118:119], v[72:73], v[6:7] op_sel:[0,1,0]
	v_pk_fma_f32 v[50:51], v[120:121], v[72:73], v[8:9] op_sel:[0,1,0]
	v_add_f32_dpp v12, v12, v12 row_ror:4 row_mask:0xf bank_mask:0xf bound_ctrl:1
	v_add_f32_dpp v103, v103, v103 row_ror:4 row_mask:0xf bank_mask:0xa
	v_add_f32_dpp v103, v83, v83 row_ror:12 row_mask:0xf bank_mask:0x5
	v_add_f32_dpp v104, v104, v104 row_ror:4 row_mask:0xf bank_mask:0xa
	v_add_f32_dpp v12, v12, v12 row_ror:8 row_mask:0xf bank_mask:0xf bound_ctrl:1
	v_pk_fma_f32 v[6:7], v[114:115], v[12:13], v[48:49] op_sel_hi:[1,0,1] neg_lo:[1,0,0] neg_hi:[1,0,0]
	v_pk_fma_f32 v[8:9], v[116:117], v[12:13], v[50:51] op_sel_hi:[1,0,1] neg_lo:[1,0,0] neg_hi:[1,0,0]
	v_pk_mul_f32 v[6:7], v[6:7], v[106:107]
	v_pk_mul_f32 v[8:9], v[8:9], v[108:109]
	s_waitcnt lgkmcnt(0)
	s_nop 0
	ds_read_b128 v[88:91], v10 offset:59648
	ds_read_b128 v[96:99], v10 offset:60160
	ds_read_b128 v[92:95], v10 offset:59904
	v_fma_mix_f32 v12, v6, v20, v180 op_sel_hi:[0,1,0]
	v_fma_mix_f32 v12, v7, v20, v12 op_sel:[0,1,0] op_sel_hi:[0,1,0]
	v_fma_mix_f32 v12, v8, v21, v12 op_sel_hi:[0,1,0]
	v_fma_mix_f32 v12, v9, v21, v12 op_sel:[0,1,0] op_sel_hi:[0,1,0]
	v_fma_mix_f32 v129, v6, v112, v180 op_sel_hi:[0,1,0]
	v_fma_mix_f32 v129, v7, v112, v129 op_sel:[0,1,0] op_sel_hi:[0,1,0]
	v_add_f32_dpp v12, v12, v12 row_ror:1 row_mask:0xf bank_mask:0xf bound_ctrl:1
	v_fma_mix_f32 v129, v8, v113, v129 op_sel_hi:[0,1,0]
	v_fma_mix_f32 v129, v9, v113, v129 op_sel:[0,1,0] op_sel_hi:[0,1,0]
	v_add_f32_dpp v12, v12, v12 row_ror:2 row_mask:0xf bank_mask:0xf bound_ctrl:1
	v_pk_fma_f32 v[48:49], v[28:29], v[66:67], v[6:7] op_sel_hi:[1,0,1]
	v_pk_fma_f32 v[50:51], v[30:31], v[66:67], v[8:9] op_sel_hi:[1,0,1]
	v_add_f32_dpp v12, v12, v12 row_ror:4 row_mask:0xf bank_mask:0xf bound_ctrl:1
	v_add_f32_dpp v104, v100, v100 row_ror:12 row_mask:0xf bank_mask:0x5
	v_add_f32_dpp v105, v105, v105 row_ror:4 row_mask:0xf bank_mask:0xa
	v_add_f32_dpp v105, v101, v101 row_ror:12 row_mask:0xf bank_mask:0x5
	v_add_f32_dpp v12, v12, v12 row_ror:8 row_mask:0xf bank_mask:0xf bound_ctrl:1
	v_pk_fma_f32 v[6:7], v[24:25], v[12:13], v[48:49] op_sel_hi:[1,0,1] neg_lo:[1,0,0] neg_hi:[1,0,0]
	v_pk_fma_f32 v[8:9], v[26:27], v[12:13], v[50:51] op_sel_hi:[1,0,1] neg_lo:[1,0,0] neg_hi:[1,0,0]
	ds_read_b128 v[110:113], v10 offset:60672
	ds_read_b128 v[106:109], v10 offset:60416
	ds_read_b128 v[118:121], v10 offset:61184
	ds_read_b128 v[114:117], v10 offset:60928
	ds_read_b128 v[70:73], v11 offset:3840
	v_fma_mix_f32 v12, v6, v36, v180 op_sel_hi:[0,1,0]
	v_fma_mix_f32 v12, v7, v36, v12 op_sel:[0,1,0] op_sel_hi:[0,1,0]
	v_fma_mix_f32 v12, v8, v37, v12 op_sel_hi:[0,1,0]
	v_fma_mix_f32 v12, v9, v37, v12 op_sel:[0,1,0] op_sel_hi:[0,1,0]
	v_fma_mix_f32 v130, v6, v22, v180 op_sel_hi:[0,1,0]
	v_fma_mix_f32 v130, v7, v22, v130 op_sel:[0,1,0] op_sel_hi:[0,1,0]
	v_add_f32_dpp v12, v12, v12 row_ror:1 row_mask:0xf bank_mask:0xf bound_ctrl:1
	v_fma_mix_f32 v130, v8, v23, v130 op_sel_hi:[0,1,0]
	v_fma_mix_f32 v130, v9, v23, v130 op_sel:[0,1,0] op_sel_hi:[0,1,0]
	v_add_f32_dpp v12, v12, v12 row_ror:2 row_mask:0xf bank_mask:0xf bound_ctrl:1
	v_pk_fma_f32 v[48:49], v[44:45], v[66:67], v[6:7] op_sel:[0,1,0]
	v_pk_fma_f32 v[50:51], v[46:47], v[66:67], v[8:9] op_sel:[0,1,0]
	v_add_f32_dpp v12, v12, v12 row_ror:4 row_mask:0xf bank_mask:0xf bound_ctrl:1
	v_add_f32_dpp v61, v61, v61 row_ror:4 row_mask:0xf bank_mask:0xa
	v_add_f32_dpp v61, v102, v102 row_ror:12 row_mask:0xf bank_mask:0x5
	v_add_f32_dpp v12, v12, v12 row_ror:8 row_mask:0xf bank_mask:0xf bound_ctrl:1
	v_pk_fma_f32 v[6:7], v[40:41], v[12:13], v[48:49] op_sel_hi:[1,0,1] neg_lo:[1,0,0] neg_hi:[1,0,0]
	v_pk_fma_f32 v[8:9], v[42:43], v[12:13], v[50:51] op_sel_hi:[1,0,1] neg_lo:[1,0,0] neg_hi:[1,0,0]
	s_waitcnt lgkmcnt(1)
	s_nop 0
	ds_read_b128 v[20:23], v10 offset:61696
	ds_read_b128 v[28:31], v10 offset:62208
	ds_read_b128 v[24:27], v10 offset:61952
	v_fma_mix_f32 v12, v6, v88, v180 op_sel_hi:[0,1,0]
	v_fma_mix_f32 v12, v7, v88, v12 op_sel:[0,1,0] op_sel_hi:[0,1,0]
	v_fma_mix_f32 v12, v8, v89, v12 op_sel_hi:[0,1,0]
	v_fma_mix_f32 v12, v9, v89, v12 op_sel:[0,1,0] op_sel_hi:[0,1,0]
	v_fma_mix_f32 v131, v6, v38, v180 op_sel_hi:[0,1,0]
	v_fma_mix_f32 v131, v7, v38, v131 op_sel:[0,1,0] op_sel_hi:[0,1,0]
	v_add_f32_dpp v12, v12, v12 row_ror:1 row_mask:0xf bank_mask:0xf bound_ctrl:1
	v_fma_mix_f32 v131, v8, v39, v131 op_sel_hi:[0,1,0]
	v_fma_mix_f32 v131, v9, v39, v131 op_sel:[0,1,0] op_sel_hi:[0,1,0]
	v_add_f32_dpp v12, v12, v12 row_ror:2 row_mask:0xf bank_mask:0xf bound_ctrl:1
	v_pk_fma_f32 v[48:49], v[96:97], v[68:69], v[6:7] op_sel_hi:[1,0,1]
	v_pk_fma_f32 v[50:51], v[98:99], v[68:69], v[8:9] op_sel_hi:[1,0,1]
	v_add_f32_dpp v12, v12, v12 row_ror:4 row_mask:0xf bank_mask:0xf bound_ctrl:1
	v_cndmask_b32_e64 v62, v105, v103, s[38:39]
	v_cndmask_b32_e64 v63, v103, v105, s[38:39]
	v_add_f32_dpp v12, v12, v12 row_ror:8 row_mask:0xf bank_mask:0xf bound_ctrl:1
	v_pk_fma_f32 v[6:7], v[92:93], v[12:13], v[48:49] op_sel_hi:[1,0,1] neg_lo:[1,0,0] neg_hi:[1,0,0]
	v_pk_fma_f32 v[8:9], v[94:95], v[12:13], v[50:51] op_sel_hi:[1,0,1] neg_lo:[1,0,0] neg_hi:[1,0,0]
	ds_read_b128 v[36:39], v10 offset:62720
	ds_read_b128 v[44:47], v10 offset:63232
	ds_read_b128 v[40:43], v10 offset:62976
	v_fma_mix_f32 v12, v6, v110, v180 op_sel_hi:[0,1,0]
	v_fma_mix_f32 v12, v7, v110, v12 op_sel:[0,1,0] op_sel_hi:[0,1,0]
	v_fma_mix_f32 v12, v8, v111, v12 op_sel_hi:[0,1,0]
	v_fma_mix_f32 v12, v9, v111, v12 op_sel:[0,1,0] op_sel_hi:[0,1,0]
	v_fma_mix_f32 v132, v6, v90, v180 op_sel_hi:[0,1,0]
	v_fma_mix_f32 v132, v7, v90, v132 op_sel:[0,1,0] op_sel_hi:[0,1,0]
	v_add_f32_dpp v12, v12, v12 row_ror:1 row_mask:0xf bank_mask:0xf bound_ctrl:1
	v_fma_mix_f32 v132, v8, v91, v132 op_sel_hi:[0,1,0]
	v_fma_mix_f32 v132, v9, v91, v132 op_sel:[0,1,0] op_sel_hi:[0,1,0]
	v_add_f32_dpp v12, v12, v12 row_ror:2 row_mask:0xf bank_mask:0xf bound_ctrl:1
	v_pk_fma_f32 v[48:49], v[118:119], v[68:69], v[6:7] op_sel:[0,1,0]
	v_pk_fma_f32 v[50:51], v[120:121], v[68:69], v[8:9] op_sel:[0,1,0]
	v_add_f32_dpp v12, v12, v12 row_ror:4 row_mask:0xf bank_mask:0xf bound_ctrl:1
	v_cndmask_b32_e64 v64, v61, v104, s[38:39]
	v_cndmask_b32_e64 v65, v104, v61, s[38:39]
	v_add_f32_dpp v12, v12, v12 row_ror:8 row_mask:0xf bank_mask:0xf bound_ctrl:1
	v_pk_fma_f32 v[6:7], v[114:115], v[12:13], v[48:49] op_sel_hi:[1,0,1] neg_lo:[1,0,0] neg_hi:[1,0,0]
	v_pk_fma_f32 v[8:9], v[116:117], v[12:13], v[50:51] op_sel_hi:[1,0,1] neg_lo:[1,0,0] neg_hi:[1,0,0]
	v_pk_mul_f32 v[6:7], v[6:7], v[106:107]
	v_pk_mul_f32 v[8:9], v[8:9], v[108:109]
	s_waitcnt lgkmcnt(0)
	s_nop 0
	ds_read_b128 v[88:91], v10 offset:63744
	ds_read_b128 v[96:99], v10 offset:64256
	ds_read_b128 v[92:95], v10 offset:64000
	v_fma_mix_f32 v12, v6, v20, v180 op_sel_hi:[0,1,0]
	v_fma_mix_f32 v12, v7, v20, v12 op_sel:[0,1,0] op_sel_hi:[0,1,0]
	v_fma_mix_f32 v12, v8, v21, v12 op_sel_hi:[0,1,0]
	v_fma_mix_f32 v12, v9, v21, v12 op_sel:[0,1,0] op_sel_hi:[0,1,0]
	v_fma_mix_f32 v133, v6, v112, v180 op_sel_hi:[0,1,0]
	v_fma_mix_f32 v133, v7, v112, v133 op_sel:[0,1,0] op_sel_hi:[0,1,0]
	v_add_f32_dpp v12, v12, v12 row_ror:1 row_mask:0xf bank_mask:0xf bound_ctrl:1
	v_fma_mix_f32 v133, v8, v113, v133 op_sel_hi:[0,1,0]
	v_fma_mix_f32 v133, v9, v113, v133 op_sel:[0,1,0] op_sel_hi:[0,1,0]
	v_add_f32_dpp v12, v12, v12 row_ror:2 row_mask:0xf bank_mask:0xf bound_ctrl:1
	v_pk_fma_f32 v[48:49], v[28:29], v[70:71], v[6:7] op_sel_hi:[1,0,1]
	v_pk_fma_f32 v[50:51], v[30:31], v[70:71], v[8:9] op_sel_hi:[1,0,1]
	v_add_f32_dpp v12, v12, v12 row_ror:4 row_mask:0xf bank_mask:0xf bound_ctrl:1
	v_add_f32_dpp v62, v63, v62 quad_perm:[2,3,0,1] row_mask:0xf bank_mask:0xf bound_ctrl:1
	v_add_f32_dpp v63, v65, v64 quad_perm:[2,3,0,1] row_mask:0xf bank_mask:0xf bound_ctrl:1
	v_add_f32_dpp v12, v12, v12 row_ror:8 row_mask:0xf bank_mask:0xf bound_ctrl:1
	v_pk_fma_f32 v[6:7], v[24:25], v[12:13], v[48:49] op_sel_hi:[1,0,1] neg_lo:[1,0,0] neg_hi:[1,0,0]
	v_pk_fma_f32 v[8:9], v[26:27], v[12:13], v[50:51] op_sel_hi:[1,0,1] neg_lo:[1,0,0] neg_hi:[1,0,0]
	ds_read_b128 v[110:113], v10 offset:64768
	ds_read_b128 v[106:109], v10 offset:64512
	ds_read_b128 v[118:121], v10 offset:65280
	ds_read_b128 v[114:117], v10 offset:65024
	v_fma_mix_f32 v12, v6, v36, v180 op_sel_hi:[0,1,0]
	v_fma_mix_f32 v12, v7, v36, v12 op_sel:[0,1,0] op_sel_hi:[0,1,0]
	v_fma_mix_f32 v12, v8, v37, v12 op_sel_hi:[0,1,0]
	v_fma_mix_f32 v12, v9, v37, v12 op_sel:[0,1,0] op_sel_hi:[0,1,0]
	v_fma_mix_f32 v134, v6, v22, v180 op_sel_hi:[0,1,0]
	v_fma_mix_f32 v134, v7, v22, v134 op_sel:[0,1,0] op_sel_hi:[0,1,0]
	v_add_f32_dpp v12, v12, v12 row_ror:1 row_mask:0xf bank_mask:0xf bound_ctrl:1
	v_fma_mix_f32 v134, v8, v23, v134 op_sel_hi:[0,1,0]
	v_fma_mix_f32 v134, v9, v23, v134 op_sel:[0,1,0] op_sel_hi:[0,1,0]
	v_add_f32_dpp v12, v12, v12 row_ror:2 row_mask:0xf bank_mask:0xf bound_ctrl:1
	v_pk_fma_f32 v[48:49], v[44:45], v[70:71], v[6:7] op_sel:[0,1,0]
	v_pk_fma_f32 v[50:51], v[46:47], v[70:71], v[8:9] op_sel:[0,1,0]
	v_add_f32_dpp v12, v12, v12 row_ror:4 row_mask:0xf bank_mask:0xf bound_ctrl:1
	v_cndmask_b32_e64 v65, v63, v62, s[40:41]
	v_cndmask_b32_e64 v62, v62, v63, s[40:41]
	v_add_f32_dpp v12, v12, v12 row_ror:8 row_mask:0xf bank_mask:0xf bound_ctrl:1
	v_pk_fma_f32 v[6:7], v[40:41], v[12:13], v[48:49] op_sel_hi:[1,0,1] neg_lo:[1,0,0] neg_hi:[1,0,0]
	v_pk_fma_f32 v[8:9], v[42:43], v[12:13], v[50:51] op_sel_hi:[1,0,1] neg_lo:[1,0,0] neg_hi:[1,0,0]
	s_waitcnt lgkmcnt(0)
	s_nop 0
	v_fma_mix_f32 v12, v6, v88, v180 op_sel_hi:[0,1,0]
	v_fma_mix_f32 v12, v7, v88, v12 op_sel:[0,1,0] op_sel_hi:[0,1,0]
	v_fma_mix_f32 v12, v8, v89, v12 op_sel_hi:[0,1,0]
	v_fma_mix_f32 v12, v9, v89, v12 op_sel:[0,1,0] op_sel_hi:[0,1,0]
	v_fma_mix_f32 v135, v6, v38, v180 op_sel_hi:[0,1,0]
	v_fma_mix_f32 v135, v7, v38, v135 op_sel:[0,1,0] op_sel_hi:[0,1,0]
	v_add_f32_dpp v12, v12, v12 row_ror:1 row_mask:0xf bank_mask:0xf bound_ctrl:1
	v_fma_mix_f32 v135, v8, v39, v135 op_sel_hi:[0,1,0]
	v_fma_mix_f32 v135, v9, v39, v135 op_sel:[0,1,0] op_sel_hi:[0,1,0]
	v_add_f32_dpp v12, v12, v12 row_ror:2 row_mask:0xf bank_mask:0xf bound_ctrl:1
	v_pk_fma_f32 v[48:49], v[96:97], v[72:73], v[6:7] op_sel_hi:[1,0,1]
	v_pk_fma_f32 v[50:51], v[98:99], v[72:73], v[8:9] op_sel_hi:[1,0,1]
	v_add_f32_dpp v12, v12, v12 row_ror:4 row_mask:0xf bank_mask:0xf bound_ctrl:1
	v_add_f32_dpp v62, v62, v65 quad_perm:[1,0,3,2] row_mask:0xf bank_mask:0xf bound_ctrl:1
	v_cvt_pk_bf16_f32 v62, v62, v62
	v_add_f32_dpp v12, v12, v12 row_ror:8 row_mask:0xf bank_mask:0xf bound_ctrl:1
	v_pk_fma_f32 v[6:7], v[92:93], v[12:13], v[48:49] op_sel_hi:[1,0,1] neg_lo:[1,0,0] neg_hi:[1,0,0]
	v_pk_fma_f32 v[8:9], v[94:95], v[12:13], v[50:51] op_sel_hi:[1,0,1] neg_lo:[1,0,0] neg_hi:[1,0,0]
	s_waitcnt lgkmcnt(0)
	s_barrier
	v_xor_b32_e32 v10, 0x10000, v10
	v_xor_b32_e32 v11, 0x1000, v11
	ds_read_b128 v[66:69], v11 offset:0
	ds_read_b128 v[20:23], v10 offset:256
	ds_read_b128 v[28:31], v10 offset:768
	ds_read_b128 v[24:27], v10 offset:512
	ds_read_b128 v[36:39], v10 offset:1280
	ds_read_b128 v[44:47], v10 offset:1792
	ds_read_b128 v[40:43], v10 offset:1536
	v_fma_mix_f32 v12, v6, v110, v180 op_sel_hi:[0,1,0]
	v_fma_mix_f32 v12, v7, v110, v12 op_sel:[0,1,0] op_sel_hi:[0,1,0]
	v_fma_mix_f32 v12, v8, v111, v12 op_sel_hi:[0,1,0]
	v_fma_mix_f32 v12, v9, v111, v12 op_sel:[0,1,0] op_sel_hi:[0,1,0]
	v_fma_mix_f32 v136, v6, v90, v180 op_sel_hi:[0,1,0]
	v_fma_mix_f32 v136, v7, v90, v136 op_sel:[0,1,0] op_sel_hi:[0,1,0]
	v_add_f32_dpp v12, v12, v12 row_ror:1 row_mask:0xf bank_mask:0xf bound_ctrl:1
	v_fma_mix_f32 v136, v8, v91, v136 op_sel_hi:[0,1,0]
	v_fma_mix_f32 v136, v9, v91, v136 op_sel:[0,1,0] op_sel_hi:[0,1,0]
	v_add_f32_dpp v12, v12, v12 row_ror:2 row_mask:0xf bank_mask:0xf bound_ctrl:1
	v_pk_fma_f32 v[48:49], v[118:119], v[72:73], v[6:7] op_sel:[0,1,0]
	v_pk_fma_f32 v[50:51], v[120:121], v[72:73], v[8:9] op_sel:[0,1,0]
	v_add_f32_dpp v12, v12, v12 row_ror:4 row_mask:0xf bank_mask:0xf bound_ctrl:1
	global_store_short v[2:3], v62, off
	v_lshl_add_u64 v[2:3], v[2:3], 0, s[84:85]
	v_add_f32_dpp v12, v12, v12 row_ror:8 row_mask:0xf bank_mask:0xf bound_ctrl:1
	v_pk_fma_f32 v[6:7], v[114:115], v[12:13], v[48:49] op_sel_hi:[1,0,1] neg_lo:[1,0,0] neg_hi:[1,0,0]
	v_pk_fma_f32 v[8:9], v[116:117], v[12:13], v[50:51] op_sel_hi:[1,0,1] neg_lo:[1,0,0] neg_hi:[1,0,0]
	v_pk_mul_f32 v[6:7], v[6:7], v[106:107]
	v_pk_mul_f32 v[8:9], v[8:9], v[108:109]
	v_fma_mix_f32 v137, v6, v112, v180 op_sel_hi:[0,1,0]
	v_fma_mix_f32 v137, v7, v112, v137 op_sel:[0,1,0] op_sel_hi:[0,1,0]
	v_fma_mix_f32 v137, v8, v113, v137 op_sel_hi:[0,1,0]
	v_fma_mix_f32 v137, v9, v113, v137 op_sel:[0,1,0] op_sel_hi:[0,1,0]
	v_mov_b32_e64 v170, v2
	v_mov_b32_e64 v171, v3
	s_mov_b64 s[100:101], -1
	s_nop 0
	s_cmp_lg_u32 s28, 0x800000
	s_cbranch_scc1 .Lscan_cons_chunk
	v_add_f32_dpp v130, v130, v130 row_ror:8 row_mask:0xf bank_mask:0xc
	v_add_f32_dpp v130, v122, v122 row_ror:8 row_mask:0xf bank_mask:0x3
	v_add_f32_dpp v131, v131, v131 row_ror:8 row_mask:0xf bank_mask:0xc
	v_add_f32_dpp v131, v123, v123 row_ror:8 row_mask:0xf bank_mask:0x3
	v_add_f32_dpp v132, v132, v132 row_ror:8 row_mask:0xf bank_mask:0xc
	v_add_f32_dpp v132, v124, v124 row_ror:8 row_mask:0xf bank_mask:0x3
	v_add_f32_dpp v133, v133, v133 row_ror:8 row_mask:0xf bank_mask:0xc
	v_add_f32_dpp v133, v125, v125 row_ror:8 row_mask:0xf bank_mask:0x3
	v_add_f32_dpp v134, v134, v134 row_ror:8 row_mask:0xf bank_mask:0xc
	v_add_f32_dpp v134, v126, v126 row_ror:8 row_mask:0xf bank_mask:0x3
	v_add_f32_dpp v135, v135, v135 row_ror:8 row_mask:0xf bank_mask:0xc
	v_add_f32_dpp v135, v127, v127 row_ror:8 row_mask:0xf bank_mask:0x3
	v_add_f32_dpp v136, v136, v136 row_ror:8 row_mask:0xf bank_mask:0xc
	v_add_f32_dpp v136, v128, v128 row_ror:8 row_mask:0xf bank_mask:0x3
	v_add_f32_dpp v137, v137, v137 row_ror:8 row_mask:0xf bank_mask:0xc
	v_add_f32_dpp v137, v129, v129 row_ror:8 row_mask:0xf bank_mask:0x3
	v_add_f32_dpp v134, v134, v134 row_ror:4 row_mask:0xf bank_mask:0xa
	v_add_f32_dpp v134, v130, v130 row_ror:12 row_mask:0xf bank_mask:0x5
	v_add_f32_dpp v135, v135, v135 row_ror:4 row_mask:0xf bank_mask:0xa
	v_add_f32_dpp v135, v131, v131 row_ror:12 row_mask:0xf bank_mask:0x5
	v_add_f32_dpp v136, v136, v136 row_ror:4 row_mask:0xf bank_mask:0xa
	v_add_f32_dpp v136, v132, v132 row_ror:12 row_mask:0xf bank_mask:0x5
	v_add_f32_dpp v137, v137, v137 row_ror:4 row_mask:0xf bank_mask:0xa
	v_add_f32_dpp v137, v133, v133 row_ror:12 row_mask:0xf bank_mask:0x5
	v_cndmask_b32_e64 v62, v136, v134, s[38:39]
	v_cndmask_b32_e64 v63, v134, v136, s[38:39]
	v_cndmask_b32_e64 v64, v137, v135, s[38:39]
	v_cndmask_b32_e64 v65, v135, v137, s[38:39]
	v_add_f32_dpp v62, v63, v62 quad_perm:[2,3,0,1] row_mask:0xf bank_mask:0xf bound_ctrl:1
	s_nop 0
	v_add_f32_dpp v63, v65, v64 quad_perm:[2,3,0,1] row_mask:0xf bank_mask:0xf bound_ctrl:1
	v_cndmask_b32_e64 v65, v63, v62, s[40:41]
	v_cndmask_b32_e64 v62, v62, v63, s[40:41]
	s_nop 1
	v_add_f32_dpp v62, v62, v65 quad_perm:[1,0,3,2] row_mask:0xf bank_mask:0xf bound_ctrl:1
	v_cvt_pk_bf16_f32 v62, v62, v62
	global_store_short v[2:3], v62, off
	s_branch .LBB0_53
